# K-loop: phases 3+4 and 7+8 merged into 32-MFMA phases (12 barriers per iteration instead of 16), reads of phases 2 and 3 drained before their first barrier
# speedup vs baseline: 1.0029x; 1.0029x over previous
; #define PG8_STAGE(bufoff, gbase, voff) do { _Pragma("unroll") for (int _i = 0; _i < 2; ++_i) \
;         __builtin_amdgcn_global_load_lds((const unsigned*)((const char*)(gbase) + (voff)[_i]), (LAS unsigned*)(lds + (bufoff) + ldsw + _i * 8192), 16, 0, 0); } while (0)
; #define PG8_LDA(dst, b, h) do { _Pragma("unroll") for (int m = 0; m < 4; ++m) _Pragma("unroll") for (int k = 0; k < 2; ++k) dst[m][k] = *(const LAS bf16x8*)(lds + PG8_SA(b, h) + aoff + m * 2048 + k * 1024); } while (0)
; #define PG8_LDB(dst, b, h) do { _Pragma("unroll") for (int n = 0; n < 2; ++n) _Pragma("unroll") for (int k = 0; k < 2; ++k) dst[n][k] = *(const LAS bf16x8*)(lds + PG8_SB(b, h) + boff + n * 2048 + k * 1024); } while (0)
; #define PG8_WAIT_V(n) asm volatile("s_waitcnt vmcnt(" #n ")" ::: "memory")
; #define PG8_WAIT_L(n) asm volatile("s_waitcnt lgkmcnt(" #n ")" ::: "memory")
; #define PG8_BAR __builtin_amdgcn_s_barrier()
; #define PG8_SCHED __builtin_amdgcn_sched_barrier(0)
; template <class Epi>
; __device__ __forceinline__ void gemm_phase(LAS unsigned char* lds, const Gemm g, const StaticOrder& S, const Epi& E) {
;     ...
;         const bool has_next = S.next(ui + 1, nxt);
;         const char* nA = has_next ? (const char*)g.A + (size_t)nxt.pm * tstepA : cA; const char* nB = has_next ? (const char*)g.Bt + (size_t)nxt.pn * tstepB : cB;
;         for (int t = 0; t < nt; t += 2) {
;             const bool last = (t == nt - 2);
;             const char* a1 = cA + (size_t)(t + 1) * kstep;
;             const char* a2 = last ? nA : cA + (size_t)(t + 2) * kstep; const char* b2 = last ? nB : cB + (size_t)(t + 2) * kstep;
;             const char* a3 = a2 + kstep; const char* b3 = b2 + kstep;
;             PG8_LDB(B0, 0, 0); PG8_SCHED; PG8_LDA(At, 0, 0); PG8_STAGE(PG8_SA(1, 1), a1 + hstepA, voffA);
;             PG8_WAIT_L(8); PG8_BAR; PG8_WAIT_L(0); PG8_MMA(0, 0, At, B0); PG8_BAR; PG8_SCHED;
;             PG8_LDB(B1, 0, 1); PG8_STAGE(PG8_SB(0, 0), b2, voffB);
;             PG8_BAR; PG8_WAIT_L(0); PG8_MMA(0, 1, At, B1); PG8_BAR;
;             PG8_LDA(At, 0, 1); PG8_STAGE(PG8_SA(0, 0), a2, voffA);
;             PG8_BAR; PG8_WAIT_L(0); PG8_MMA(1, 0, At, B0); PG8_BAR; PG8_SCHED;
;             PG8_STAGE(PG8_SB(0, 1), b2 + hstepB, voffB);
;             PG8_WAIT_V(6); PG8_BAR; PG8_MMA(1, 1, At, B1); PG8_BAR;
.LBB0_140:
	v_mov_b64_e32 v[0:1], 0x800
	s_ashr_i32 s15, s14, 31
	v_cmp_lt_i64_e32 vcc, s[16:17], v[0:1]
	s_lshl_b64 s[16:17], s[14:15], 20
	v_readlane_b32 s18, v252, 53
	v_readlane_b32 s19, v252, 54
	s_add_u32 s16, s18, s16
	s_addc_u32 s17, s19, s17
	s_and_b64 s[18:19], vcc, exec
	s_cselect_b32 s15, s17, s23
	s_cselect_b32 s49, s16, s22
	s_ashr_i32 s5, s4, 31
	s_lshl_b64 s[18:19], s[4:5], 20
	s_add_u32 s18, s34, s18
	s_addc_u32 s19, s35, s19
	s_and_b64 s[26:27], vcc, exec
	s_cselect_b32 s5, s19, s25
	s_cselect_b32 s50, s18, s24
	s_add_u32 s22, s22, 0x84000
	s_addc_u32 s23, s23, 0
	s_add_u32 s51, s24, 0x8000
	s_addc_u32 s52, s25, 0
	s_mov_b32 s54, -2
	s_add_u32 s24, s22, 0xfff84000
	s_addc_u32 s25, s23, -1
	s_cmp_eq_u32 s54, 28
	s_cselect_b32 s28, s49, s24
	s_cselect_b32 s29, s15, s25
	s_cselect_b32 s24, s50, s51
	s_cselect_b32 s25, s5, s52
	s_add_u32 s26, s28, 0x4000
	s_addc_u32 s27, s29, 0
	s_add_i32 s55, 0, 0x10000
	v_add_u32_e32 v148, s55, v134
	ds_read_b128 v[136:139], v148
	ds_read_b128 v[144:147], v148 offset:2048
	ds_read_b128 v[140:143], v148 offset:1024
	ds_read_b128 v[148:151], v148 offset:3072
	v_lshl_add_u64 v[188:189], s[22:23], 0, v[128:129]
	s_add_i32 m0, s37, 0xc000
	ds_read_b128 v[156:159], v135
	ds_read_b128 v[164:167], v135 offset:2048
	ds_read_b128 v[172:175], v135 offset:4096
	ds_read_b128 v[180:183], v135 offset:6144
	ds_read_b128 v[160:163], v135 offset:1024
	ds_read_b128 v[168:171], v135 offset:3072
	ds_read_b128 v[176:179], v135 offset:5120
	ds_read_b128 v[184:187], v135 offset:7168
	global_load_lds_dwordx4 v[188:189], off
	s_add_i32 m0, s37, 0xe000
	v_lshl_add_u64 v[188:189], s[22:23], 0, v[130:131]
	global_load_lds_dwordx4 v[188:189], off
	s_waitcnt lgkmcnt(8)
	s_barrier
	s_waitcnt lgkmcnt(7)
	v_mfma_f32_16x16x32_bf16 v[124:127], v[136:139], v[156:159], 0
	s_setprio 1
	v_mfma_f32_16x16x32_bf16 v[120:123], v[144:147], v[156:159], 0
	s_waitcnt lgkmcnt(6)
	v_mfma_f32_16x16x32_bf16 v[108:111], v[136:139], v[164:167], 0
	v_mfma_f32_16x16x32_bf16 v[104:107], v[144:147], v[164:167], 0
	s_waitcnt lgkmcnt(5)
	v_mfma_f32_16x16x32_bf16 v[92:95], v[136:139], v[172:175], 0
	v_mfma_f32_16x16x32_bf16 v[88:91], v[144:147], v[172:175], 0
	s_waitcnt lgkmcnt(4)
	v_mfma_f32_16x16x32_bf16 v[76:79], v[136:139], v[180:183], 0
	v_mfma_f32_16x16x32_bf16 v[72:75], v[144:147], v[180:183], 0
	s_waitcnt lgkmcnt(3)
	v_mfma_f32_16x16x32_bf16 v[124:127], v[140:143], v[160:163], v[124:127]
	v_mfma_f32_16x16x32_bf16 v[120:123], v[148:151], v[160:163], v[120:123]
	s_waitcnt lgkmcnt(2)
	v_mfma_f32_16x16x32_bf16 v[108:111], v[140:143], v[168:171], v[108:111]
	v_mfma_f32_16x16x32_bf16 v[104:107], v[148:151], v[168:171], v[104:107]
	s_waitcnt lgkmcnt(1)
	v_mfma_f32_16x16x32_bf16 v[92:95], v[140:143], v[176:179], v[92:95]
	v_mfma_f32_16x16x32_bf16 v[88:91], v[148:151], v[176:179], v[88:91]
	s_waitcnt lgkmcnt(0)
	v_mfma_f32_16x16x32_bf16 v[76:79], v[140:143], v[184:187], v[76:79]
	s_setprio 0
	v_mfma_f32_16x16x32_bf16 v[72:75], v[148:151], v[184:187], v[72:75]
	s_barrier
	s_add_i32 s58, 0, 0x14000
	s_add_i32 s55, s55, s36
	v_add_u32_e32 v152, s58, v134
	v_lshl_add_u64 v[204:205], s[24:25], 0, v[128:129]
	s_mov_b32 m0, s55
	ds_read_b128 v[188:191], v152
	ds_read_b128 v[196:199], v152 offset:2048
	ds_read_b128 v[192:195], v152 offset:1024
	ds_read_b128 v[200:203], v152 offset:3072
	global_load_lds_dwordx4 v[204:205], off
	s_add_i32 m0, s55, 0x2000
	v_lshl_add_u64 v[204:205], s[24:25], 0, v[130:131]
	global_load_lds_dwordx4 v[204:205], off
	s_waitcnt lgkmcnt(0)
	s_barrier
	v_mfma_f32_16x16x32_bf16 v[116:119], v[188:191], v[156:159], 0
	s_setprio 1
	v_mfma_f32_16x16x32_bf16 v[112:115], v[196:199], v[156:159], 0
	s_mov_b32 m0, s37
	v_lshl_add_u64 v[204:205], s[28:29], 0, v[128:129]
	v_mfma_f32_16x16x32_bf16 v[100:103], v[188:191], v[164:167], 0
	v_mfma_f32_16x16x32_bf16 v[96:99], v[196:199], v[164:167], 0
	v_mfma_f32_16x16x32_bf16 v[84:87], v[188:191], v[172:175], 0
	v_mfma_f32_16x16x32_bf16 v[80:83], v[196:199], v[172:175], 0
	v_mfma_f32_16x16x32_bf16 v[68:71], v[188:191], v[180:183], 0
	v_mfma_f32_16x16x32_bf16 v[64:67], v[196:199], v[180:183], 0
	v_mfma_f32_16x16x32_bf16 v[116:119], v[192:195], v[160:163], v[116:119]
	v_mfma_f32_16x16x32_bf16 v[112:115], v[200:203], v[160:163], v[112:115]
	v_mfma_f32_16x16x32_bf16 v[100:103], v[192:195], v[168:171], v[100:103]
	v_mfma_f32_16x16x32_bf16 v[96:99], v[200:203], v[168:171], v[96:99]
	v_mfma_f32_16x16x32_bf16 v[84:87], v[192:195], v[176:179], v[84:87]
	v_mfma_f32_16x16x32_bf16 v[80:83], v[200:203], v[176:179], v[80:83]
	v_mfma_f32_16x16x32_bf16 v[68:71], v[192:195], v[184:187], v[68:71]
	s_setprio 0
	v_mfma_f32_16x16x32_bf16 v[64:67], v[200:203], v[184:187], v[64:67]
	s_barrier
	ds_read_b128 v[156:159], v135 offset:16384
	ds_read_b128 v[164:167], v135 offset:18432
	ds_read_b128 v[172:175], v135 offset:20480
	ds_read_b128 v[180:183], v135 offset:22528
	ds_read_b128 v[160:163], v135 offset:17408
	ds_read_b128 v[168:171], v135 offset:19456
	ds_read_b128 v[176:179], v135 offset:21504
	ds_read_b128 v[184:187], v135 offset:23552
	global_load_lds_dwordx4 v[204:205], off
	s_mov_b32 m0, s38
	v_lshl_add_u64 v[204:205], s[28:29], 0, v[130:131]
	global_load_lds_dwordx4 v[204:205], off
	s_add_u32 s56, s24, 0x80000
	s_addc_u32 s57, s25, 0
	s_add_i32 s55, s58, s36
	s_mov_b32 m0, s55
	v_lshl_add_u64 v[204:205], s[56:57], 0, v[128:129]
	global_load_lds_dwordx4 v[204:205], off
	s_add_i32 m0, s55, 0x2000
	v_lshl_add_u64 v[204:205], s[56:57], 0, v[130:131]
	global_load_lds_dwordx4 v[204:205], off
	s_waitcnt vmcnt(6)
	s_waitcnt lgkmcnt(0)
	s_barrier
; #define PG8_STAGE(bufoff, gbase, voff) do { _Pragma("unroll") for (int _i = 0; _i < 2; ++_i) \
;         __builtin_amdgcn_global_load_lds((const unsigned*)((const char*)(gbase) + (voff)[_i]), (LAS unsigned*)(lds + (bufoff) + ldsw + _i * 8192), 16, 0, 0); } while (0)
; #define PG8_LDA(dst, b, h) do { _Pragma("unroll") for (int m = 0; m < 4; ++m) _Pragma("unroll") for (int k = 0; k < 2; ++k) dst[m][k] = *(const LAS bf16x8*)(lds + PG8_SA(b, h) + aoff + m * 2048 + k * 1024); } while (0)
; #define PG8_LDB(dst, b, h) do { _Pragma("unroll") for (int n = 0; n < 2; ++n) _Pragma("unroll") for (int k = 0; k < 2; ++k) dst[n][k] = *(const LAS bf16x8*)(lds + PG8_SB(b, h) + boff + n * 2048 + k * 1024); } while (0)
; #define PG8_MMA(ai, bj, At, Bt) do { __builtin_amdgcn_s_setprio(1); _Pragma("unroll") for (int m = 0; m < 4; ++m) _Pragma("unroll") for (int n = 0; n < 2; ++n) _Pragma("unroll") for (int k = 0; k < 2; ++k) \
;         acc[ai][bj][m][n] = __builtin_amdgcn_mfma_f32_16x16x32_bf16(Bt[n][k], At[m][k], acc[ai][bj][m][n], 0, 0, 0); __builtin_amdgcn_s_setprio(0); } while (0)
; #define PG8_WAIT_V(n) asm volatile("s_waitcnt vmcnt(" #n ")" ::: "memory")
; #define PG8_WAIT_L(n) asm volatile("s_waitcnt lgkmcnt(" #n ")" ::: "memory")
; #define PG8_BAR __builtin_amdgcn_s_barrier()
; #define PG8_SCHED __builtin_amdgcn_sched_barrier(0)
; template <class Epi>
; __device__ __forceinline__ void gemm_phase(LAS unsigned char* lds, const Gemm g, const StaticOrder& S, const Epi& E) {
;     ...
;             PG8_BAR; PG8_WAIT_L(0); PG8_MMA(1, 0, At, B0); PG8_BAR; PG8_SCHED;
;             PG8_STAGE(PG8_SB(0, 1), b2 + hstepB, voffB);
;             PG8_WAIT_V(6); PG8_BAR; PG8_MMA(1, 1, At, B1); PG8_BAR;
;             PG8_LDB(B0, 1, 0); PG8_SCHED; PG8_LDA(At, 1, 0); PG8_STAGE(PG8_SA(0, 1), a2 + hstepA, voffA);
;             PG8_WAIT_L(8); PG8_BAR; PG8_WAIT_L(0); PG8_MMA(0, 0, At, B0); PG8_BAR; PG8_SCHED;
;             PG8_LDB(B1, 1, 1); PG8_STAGE(PG8_SB(1, 0), b3, voffB);
;             PG8_BAR; PG8_WAIT_L(0); PG8_MMA(0, 1, At, B1); PG8_BAR;
	v_mfma_f32_16x16x32_bf16 v[60:63], v[136:139], v[156:159], 0
	s_setprio 1
	v_mfma_f32_16x16x32_bf16 v[56:59], v[144:147], v[156:159], 0
	v_mfma_f32_16x16x32_bf16 v[44:47], v[136:139], v[164:167], 0
	v_mfma_f32_16x16x32_bf16 v[40:43], v[144:147], v[164:167], 0
	v_mfma_f32_16x16x32_bf16 v[28:31], v[136:139], v[172:175], 0
	v_mfma_f32_16x16x32_bf16 v[24:27], v[144:147], v[172:175], 0
	v_mfma_f32_16x16x32_bf16 v[12:15], v[136:139], v[180:183], 0
	v_mfma_f32_16x16x32_bf16 v[8:11], v[144:147], v[180:183], 0
	v_mfma_f32_16x16x32_bf16 v[60:63], v[140:143], v[160:163], v[60:63]
	v_mfma_f32_16x16x32_bf16 v[56:59], v[148:151], v[160:163], v[56:59]
	v_mfma_f32_16x16x32_bf16 v[44:47], v[140:143], v[168:171], v[44:47]
	v_mfma_f32_16x16x32_bf16 v[40:43], v[148:151], v[168:171], v[40:43]
	v_mfma_f32_16x16x32_bf16 v[28:31], v[140:143], v[176:179], v[28:31]
	v_mfma_f32_16x16x32_bf16 v[24:27], v[148:151], v[176:179], v[24:27]
	v_mfma_f32_16x16x32_bf16 v[12:15], v[140:143], v[184:187], v[12:15]
	v_mfma_f32_16x16x32_bf16 v[8:11], v[148:151], v[184:187], v[8:11]
	v_mfma_f32_16x16x32_bf16 v[52:55], v[188:191], v[156:159], 0
	v_mfma_f32_16x16x32_bf16 v[48:51], v[196:199], v[156:159], 0
	s_add_i32 s55, 0, 0x18000
	v_add_u32_e32 v148, s55, v134
	v_mfma_f32_16x16x32_bf16 v[36:39], v[188:191], v[164:167], 0
	v_mfma_f32_16x16x32_bf16 v[32:35], v[196:199], v[164:167], 0
	v_mfma_f32_16x16x32_bf16 v[20:23], v[188:191], v[172:175], 0
	v_mfma_f32_16x16x32_bf16 v[16:19], v[196:199], v[172:175], 0
	v_mfma_f32_16x16x32_bf16 v[4:7], v[188:191], v[180:183], 0
	v_mfma_f32_16x16x32_bf16 v[0:3], v[196:199], v[180:183], 0
	v_mfma_f32_16x16x32_bf16 v[52:55], v[192:195], v[160:163], v[52:55]
	v_mfma_f32_16x16x32_bf16 v[48:51], v[200:203], v[160:163], v[48:51]
	v_mfma_f32_16x16x32_bf16 v[36:39], v[192:195], v[168:171], v[36:39]
	v_mfma_f32_16x16x32_bf16 v[32:35], v[200:203], v[168:171], v[32:35]
	v_mfma_f32_16x16x32_bf16 v[20:23], v[192:195], v[176:179], v[20:23]
	v_mfma_f32_16x16x32_bf16 v[16:19], v[200:203], v[176:179], v[16:19]
	v_mfma_f32_16x16x32_bf16 v[4:7], v[192:195], v[184:187], v[4:7]
	s_setprio 0
	v_mfma_f32_16x16x32_bf16 v[0:3], v[200:203], v[184:187], v[0:3]
	s_barrier
	ds_read_b128 v[136:139], v148
	ds_read_b128 v[144:147], v148 offset:2048
	ds_read_b128 v[140:143], v148 offset:1024
	ds_read_b128 v[148:151], v148 offset:3072
	s_add_u32 s28, s28, 0x80000
	s_addc_u32 s29, s29, 0
	s_mov_b32 m0, s39
	v_lshl_add_u64 v[188:189], s[28:29], 0, v[128:129]
	ds_read_b128 v[156:159], v135 offset:32768
	ds_read_b128 v[164:167], v135 offset:34816
	ds_read_b128 v[172:175], v135 offset:36864
	ds_read_b128 v[180:183], v135 offset:38912
	ds_read_b128 v[160:163], v135 offset:33792
	ds_read_b128 v[168:171], v135 offset:35840
	ds_read_b128 v[176:179], v135 offset:37888
	ds_read_b128 v[184:187], v135 offset:39936
	global_load_lds_dwordx4 v[188:189], off
	s_mov_b32 m0, s40
	v_lshl_add_u64 v[188:189], s[28:29], 0, v[130:131]
	global_load_lds_dwordx4 v[188:189], off
	s_waitcnt lgkmcnt(8)
	s_barrier
	s_waitcnt lgkmcnt(7)
	v_mfma_f32_16x16x32_bf16 v[124:127], v[136:139], v[156:159], v[124:127]
	s_setprio 1
	v_mfma_f32_16x16x32_bf16 v[120:123], v[144:147], v[156:159], v[120:123]
	s_waitcnt lgkmcnt(6)
	v_mfma_f32_16x16x32_bf16 v[108:111], v[136:139], v[164:167], v[108:111]
	v_mfma_f32_16x16x32_bf16 v[104:107], v[144:147], v[164:167], v[104:107]
	s_waitcnt lgkmcnt(5)
	v_mfma_f32_16x16x32_bf16 v[92:95], v[136:139], v[172:175], v[92:95]
	v_mfma_f32_16x16x32_bf16 v[88:91], v[144:147], v[172:175], v[88:91]
	s_waitcnt lgkmcnt(4)
	v_mfma_f32_16x16x32_bf16 v[76:79], v[136:139], v[180:183], v[76:79]
	v_mfma_f32_16x16x32_bf16 v[72:75], v[144:147], v[180:183], v[72:75]
	s_waitcnt lgkmcnt(3)
	v_mfma_f32_16x16x32_bf16 v[124:127], v[140:143], v[160:163], v[124:127]
	v_mfma_f32_16x16x32_bf16 v[120:123], v[148:151], v[160:163], v[120:123]
	s_waitcnt lgkmcnt(2)
	v_mfma_f32_16x16x32_bf16 v[108:111], v[140:143], v[168:171], v[108:111]
	v_mfma_f32_16x16x32_bf16 v[104:107], v[148:151], v[168:171], v[104:107]
	s_waitcnt lgkmcnt(1)
	v_mfma_f32_16x16x32_bf16 v[92:95], v[140:143], v[176:179], v[92:95]
	v_mfma_f32_16x16x32_bf16 v[88:91], v[148:151], v[176:179], v[88:91]
	s_waitcnt lgkmcnt(0)
	v_mfma_f32_16x16x32_bf16 v[76:79], v[140:143], v[184:187], v[76:79]
	s_setprio 0
	v_mfma_f32_16x16x32_bf16 v[72:75], v[148:151], v[184:187], v[72:75]
	s_barrier
	s_add_i32 s56, 0, 0x1c000
	s_add_u32 s28, s24, 0x4000
	s_addc_u32 s29, s25, 0
	s_add_i32 s55, s55, s36
	v_add_u32_e32 v152, s56, v134
	v_lshl_add_u64 v[204:205], s[28:29], 0, v[128:129]
	s_mov_b32 m0, s55
	ds_read_b128 v[188:191], v152
	ds_read_b128 v[196:199], v152 offset:2048
	ds_read_b128 v[192:195], v152 offset:1024
	ds_read_b128 v[200:203], v152 offset:3072
	global_load_lds_dwordx4 v[204:205], off
	s_add_i32 m0, s55, 0x2000
	v_lshl_add_u64 v[204:205], s[28:29], 0, v[130:131]
	global_load_lds_dwordx4 v[204:205], off
	s_waitcnt lgkmcnt(0)
	s_barrier
	v_mfma_f32_16x16x32_bf16 v[116:119], v[188:191], v[156:159], v[116:119]
	s_setprio 1
	v_mfma_f32_16x16x32_bf16 v[112:115], v[196:199], v[156:159], v[112:115]
	s_mov_b32 m0, s43
	v_lshl_add_u64 v[204:205], s[26:27], 0, v[128:129]
	v_mfma_f32_16x16x32_bf16 v[100:103], v[188:191], v[164:167], v[100:103]
	v_mfma_f32_16x16x32_bf16 v[96:99], v[196:199], v[164:167], v[96:99]
	v_mfma_f32_16x16x32_bf16 v[84:87], v[188:191], v[172:175], v[84:87]
	v_mfma_f32_16x16x32_bf16 v[80:83], v[196:199], v[172:175], v[80:83]
	v_mfma_f32_16x16x32_bf16 v[68:71], v[188:191], v[180:183], v[68:71]
	v_mfma_f32_16x16x32_bf16 v[64:67], v[196:199], v[180:183], v[64:67]
	v_mfma_f32_16x16x32_bf16 v[116:119], v[192:195], v[160:163], v[116:119]
	v_mfma_f32_16x16x32_bf16 v[112:115], v[200:203], v[160:163], v[112:115]
	v_mfma_f32_16x16x32_bf16 v[100:103], v[192:195], v[168:171], v[100:103]
	v_mfma_f32_16x16x32_bf16 v[96:99], v[200:203], v[168:171], v[96:99]
	v_mfma_f32_16x16x32_bf16 v[84:87], v[192:195], v[176:179], v[84:87]
	v_mfma_f32_16x16x32_bf16 v[80:83], v[200:203], v[176:179], v[80:83]
	v_mfma_f32_16x16x32_bf16 v[68:71], v[192:195], v[184:187], v[68:71]
	s_setprio 0
	v_mfma_f32_16x16x32_bf16 v[64:67], v[200:203], v[184:187], v[64:67]
	s_barrier
; #define PG8_STAGE(bufoff, gbase, voff) do { _Pragma("unroll") for (int _i = 0; _i < 2; ++_i) \
;         __builtin_amdgcn_global_load_lds((const unsigned*)((const char*)(gbase) + (voff)[_i]), (LAS unsigned*)(lds + (bufoff) + ldsw + _i * 8192), 16, 0, 0); } while (0)
; #define PG8_LDA(dst, b, h) do { _Pragma("unroll") for (int m = 0; m < 4; ++m) _Pragma("unroll") for (int k = 0; k < 2; ++k) dst[m][k] = *(const LAS bf16x8*)(lds + PG8_SA(b, h) + aoff + m * 2048 + k * 1024); } while (0)
; #define PG8_WAIT_V(n) asm volatile("s_waitcnt vmcnt(" #n ")" ::: "memory")
; #define PG8_WAIT_L(n) asm volatile("s_waitcnt lgkmcnt(" #n ")" ::: "memory")
; template <class Epi>
; __device__ __forceinline__ void gemm_phase(LAS unsigned char* lds, const Gemm g, const StaticOrder& S, const Epi& E) {
;     ...
;         for (int t = 0; t < nt; t += 2) {
;             const bool last = (t == nt - 2);
;             const char* a1 = cA + (size_t)(t + 1) * kstep;
;             const char* a2 = last ? nA : cA + (size_t)(t + 2) * kstep; const char* b2 = last ? nB : cB + (size_t)(t + 2) * kstep;
;             const char* a3 = a2 + kstep; const char* b3 = b2 + kstep;
;             PG8_LDB(B0, 0, 0); PG8_SCHED; PG8_LDA(At, 0, 0); PG8_STAGE(PG8_SA(1, 1), a1 + hstepA, voffA);
;             PG8_WAIT_L(8); PG8_BAR; PG8_WAIT_L(0); PG8_MMA(0, 0, At, B0); PG8_BAR; PG8_SCHED;
;             PG8_LDB(B1, 0, 1); PG8_STAGE(PG8_SB(0, 0), b2, voffB);
;             PG8_BAR; PG8_WAIT_L(0); PG8_MMA(0, 1, At, B1); PG8_BAR;
;             PG8_LDA(At, 0, 1); PG8_STAGE(PG8_SA(0, 0), a2, voffA);
;             PG8_BAR; PG8_WAIT_L(0); PG8_MMA(1, 0, At, B0); PG8_BAR; PG8_SCHED;
;             PG8_STAGE(PG8_SB(0, 1), b2 + hstepB, voffB);
;             PG8_WAIT_V(6); PG8_BAR; PG8_MMA(1, 1, At, B1); PG8_BAR;
;             PG8_LDB(B0, 1, 0); PG8_SCHED; PG8_LDA(At, 1, 0); PG8_STAGE(PG8_SA(0, 1), a2 + hstepA, voffA);
;             PG8_WAIT_L(8); PG8_BAR; PG8_WAIT_L(0); PG8_MMA(0, 0, At, B0); PG8_BAR; PG8_SCHED;
;             PG8_LDB(B1, 1, 1); PG8_STAGE(PG8_SB(1, 0), b3, voffB);
;             PG8_BAR; PG8_WAIT_L(0); PG8_MMA(0, 1, At, B1); PG8_BAR;
;             PG8_LDA(At, 1, 1); PG8_STAGE(PG8_SA(1, 0), a3, voffA);
;             PG8_BAR; PG8_WAIT_L(0); PG8_MMA(1, 0, At, B0); PG8_BAR; PG8_SCHED;
;             PG8_STAGE(PG8_SB(1, 1), b3 + hstepB, voffB);
;             PG8_WAIT_V(6); PG8_BAR; PG8_MMA(1, 1, At, B1); PG8_BAR;
	ds_read_b128 v[156:159], v135 offset:49152
	ds_read_b128 v[164:167], v135 offset:51200
	ds_read_b128 v[172:175], v135 offset:53248
	ds_read_b128 v[180:183], v135 offset:55296
	ds_read_b128 v[160:163], v135 offset:50176
	ds_read_b128 v[168:171], v135 offset:52224
	ds_read_b128 v[176:179], v135 offset:54272
	ds_read_b128 v[184:187], v135 offset:56320
	global_load_lds_dwordx4 v[204:205], off
	s_mov_b32 m0, s44
	v_lshl_add_u64 v[204:205], s[26:27], 0, v[130:131]
	global_load_lds_dwordx4 v[204:205], off
	s_add_u32 s24, s24, 0x84000
	s_addc_u32 s25, s25, 0
	s_add_i32 s26, s56, s36
	s_mov_b32 m0, s26
	v_lshl_add_u64 v[204:205], s[24:25], 0, v[128:129]
	global_load_lds_dwordx4 v[204:205], off
	s_add_i32 m0, s26, 0x2000
	v_lshl_add_u64 v[204:205], s[24:25], 0, v[130:131]
	global_load_lds_dwordx4 v[204:205], off
	s_waitcnt vmcnt(6)
	s_waitcnt lgkmcnt(0)
	s_barrier
	v_mfma_f32_16x16x32_bf16 v[60:63], v[136:139], v[156:159], v[60:63]
	s_setprio 1
	v_mfma_f32_16x16x32_bf16 v[56:59], v[144:147], v[156:159], v[56:59]
	v_mfma_f32_16x16x32_bf16 v[44:47], v[136:139], v[164:167], v[44:47]
	v_mfma_f32_16x16x32_bf16 v[40:43], v[144:147], v[164:167], v[40:43]
	v_mfma_f32_16x16x32_bf16 v[28:31], v[136:139], v[172:175], v[28:31]
	v_mfma_f32_16x16x32_bf16 v[24:27], v[144:147], v[172:175], v[24:27]
	v_mfma_f32_16x16x32_bf16 v[12:15], v[136:139], v[180:183], v[12:15]
	v_mfma_f32_16x16x32_bf16 v[8:11], v[144:147], v[180:183], v[8:11]
	v_mfma_f32_16x16x32_bf16 v[60:63], v[140:143], v[160:163], v[60:63]
	v_mfma_f32_16x16x32_bf16 v[56:59], v[148:151], v[160:163], v[56:59]
	v_mfma_f32_16x16x32_bf16 v[44:47], v[140:143], v[168:171], v[44:47]
	v_mfma_f32_16x16x32_bf16 v[40:43], v[148:151], v[168:171], v[40:43]
	v_mfma_f32_16x16x32_bf16 v[28:31], v[140:143], v[176:179], v[28:31]
	v_mfma_f32_16x16x32_bf16 v[24:27], v[148:151], v[176:179], v[24:27]
	v_mfma_f32_16x16x32_bf16 v[12:15], v[140:143], v[184:187], v[12:15]
	v_mfma_f32_16x16x32_bf16 v[8:11], v[148:151], v[184:187], v[8:11]
	v_mfma_f32_16x16x32_bf16 v[52:55], v[188:191], v[156:159], v[52:55]
	v_mfma_f32_16x16x32_bf16 v[48:51], v[196:199], v[156:159], v[48:51]
	s_add_i32 s54, s54, 2
	s_add_u32 s22, s22, 0x8000
	s_addc_u32 s23, s23, 0
	s_add_u32 s51, s51, 0x8000
	s_addc_u32 s52, s52, 0
	v_mfma_f32_16x16x32_bf16 v[36:39], v[188:191], v[164:167], v[36:39]
	v_mfma_f32_16x16x32_bf16 v[32:35], v[196:199], v[164:167], v[32:35]
	v_mfma_f32_16x16x32_bf16 v[20:23], v[188:191], v[172:175], v[20:23]
	v_mfma_f32_16x16x32_bf16 v[16:19], v[196:199], v[172:175], v[16:19]
	v_mfma_f32_16x16x32_bf16 v[4:7], v[188:191], v[180:183], v[4:7]
	v_mfma_f32_16x16x32_bf16 v[0:3], v[196:199], v[180:183], v[0:3]
	v_mfma_f32_16x16x32_bf16 v[52:55], v[192:195], v[160:163], v[52:55]
	v_mfma_f32_16x16x32_bf16 v[48:51], v[200:203], v[160:163], v[48:51]
	v_mfma_f32_16x16x32_bf16 v[36:39], v[192:195], v[168:171], v[36:39]
	v_mfma_f32_16x16x32_bf16 v[32:35], v[200:203], v[168:171], v[32:35]
	v_mfma_f32_16x16x32_bf16 v[20:23], v[192:195], v[176:179], v[20:23]
	v_mfma_f32_16x16x32_bf16 v[16:19], v[200:203], v[176:179], v[16:19]
	v_mfma_f32_16x16x32_bf16 v[4:7], v[192:195], v[184:187], v[4:7]
	s_cmp_gt_u32 s54, 29
	s_setprio 0
	v_mfma_f32_16x16x32_bf16 v[0:3], v[200:203], v[184:187], v[0:3]
	s_barrier
	s_cbranch_scc0 .LBB0_141
	s_branch .Lpeel_done_141
.LBB0_141:
	s_add_u32 s24, s22, 0xfff84000
	s_addc_u32 s25, s23, -1
	s_cmp_eq_u32 s54, 28
	s_cselect_b32 s28, s49, s24
	s_cselect_b32 s29, s15, s25
	s_cselect_b32 s24, s50, s51
	s_cselect_b32 s25, s5, s52
	s_add_u32 s26, s28, 0x4000
	s_addc_u32 s27, s29, 0
	s_add_i32 s55, 0, 0x10000
	v_add_u32_e32 v148, s55, v134
	ds_read_b128 v[136:139], v148
	ds_read_b128 v[144:147], v148 offset:2048
	ds_read_b128 v[140:143], v148 offset:1024
	ds_read_b128 v[148:151], v148 offset:3072
	v_lshl_add_u64 v[188:189], s[22:23], 0, v[128:129]
	s_add_i32 m0, s37, 0xc000
	ds_read_b128 v[156:159], v135
	ds_read_b128 v[164:167], v135 offset:2048
	ds_read_b128 v[172:175], v135 offset:4096
	ds_read_b128 v[180:183], v135 offset:6144
	ds_read_b128 v[160:163], v135 offset:1024
	ds_read_b128 v[168:171], v135 offset:3072
	ds_read_b128 v[176:179], v135 offset:5120
	ds_read_b128 v[184:187], v135 offset:7168
	global_load_lds_dwordx4 v[188:189], off
	s_add_i32 m0, s37, 0xe000
	v_lshl_add_u64 v[188:189], s[22:23], 0, v[130:131]
	global_load_lds_dwordx4 v[188:189], off
	s_waitcnt lgkmcnt(8)
	s_barrier
	s_waitcnt lgkmcnt(7)
	v_mfma_f32_16x16x32_bf16 v[124:127], v[136:139], v[156:159], v[124:127]
	s_setprio 1
	v_mfma_f32_16x16x32_bf16 v[120:123], v[144:147], v[156:159], v[120:123]
	s_waitcnt lgkmcnt(6)
	v_mfma_f32_16x16x32_bf16 v[108:111], v[136:139], v[164:167], v[108:111]
	v_mfma_f32_16x16x32_bf16 v[104:107], v[144:147], v[164:167], v[104:107]
	s_waitcnt lgkmcnt(5)
	v_mfma_f32_16x16x32_bf16 v[92:95], v[136:139], v[172:175], v[92:95]
	v_mfma_f32_16x16x32_bf16 v[88:91], v[144:147], v[172:175], v[88:91]
	s_waitcnt lgkmcnt(4)
	v_mfma_f32_16x16x32_bf16 v[76:79], v[136:139], v[180:183], v[76:79]
	v_mfma_f32_16x16x32_bf16 v[72:75], v[144:147], v[180:183], v[72:75]
	s_waitcnt lgkmcnt(3)
	v_mfma_f32_16x16x32_bf16 v[124:127], v[140:143], v[160:163], v[124:127]
	v_mfma_f32_16x16x32_bf16 v[120:123], v[148:151], v[160:163], v[120:123]
	s_waitcnt lgkmcnt(2)
	v_mfma_f32_16x16x32_bf16 v[108:111], v[140:143], v[168:171], v[108:111]
	v_mfma_f32_16x16x32_bf16 v[104:107], v[148:151], v[168:171], v[104:107]
	s_waitcnt lgkmcnt(1)
	v_mfma_f32_16x16x32_bf16 v[92:95], v[140:143], v[176:179], v[92:95]
	v_mfma_f32_16x16x32_bf16 v[88:91], v[148:151], v[176:179], v[88:91]
	s_waitcnt lgkmcnt(0)
	v_mfma_f32_16x16x32_bf16 v[76:79], v[140:143], v[184:187], v[76:79]
	s_setprio 0
	v_mfma_f32_16x16x32_bf16 v[72:75], v[148:151], v[184:187], v[72:75]
	s_barrier
; #define PG8_STAGE(bufoff, gbase, voff) do { _Pragma("unroll") for (int _i = 0; _i < 2; ++_i) \
;         __builtin_amdgcn_global_load_lds((const unsigned*)((const char*)(gbase) + (voff)[_i]), (LAS unsigned*)(lds + (bufoff) + ldsw + _i * 8192), 16, 0, 0); } while (0)
; #define PG8_LDA(dst, b, h) do { _Pragma("unroll") for (int m = 0; m < 4; ++m) _Pragma("unroll") for (int k = 0; k < 2; ++k) dst[m][k] = *(const LAS bf16x8*)(lds + PG8_SA(b, h) + aoff + m * 2048 + k * 1024); } while (0)
; #define PG8_LDB(dst, b, h) do { _Pragma("unroll") for (int n = 0; n < 2; ++n) _Pragma("unroll") for (int k = 0; k < 2; ++k) dst[n][k] = *(const LAS bf16x8*)(lds + PG8_SB(b, h) + boff + n * 2048 + k * 1024); } while (0)
; #define PG8_MMA(ai, bj, At, Bt) do { __builtin_amdgcn_s_setprio(1); _Pragma("unroll") for (int m = 0; m < 4; ++m) _Pragma("unroll") for (int n = 0; n < 2; ++n) _Pragma("unroll") for (int k = 0; k < 2; ++k) \
;         acc[ai][bj][m][n] = __builtin_amdgcn_mfma_f32_16x16x32_bf16(Bt[n][k], At[m][k], acc[ai][bj][m][n], 0, 0, 0); __builtin_amdgcn_s_setprio(0); } while (0)
; #define PG8_WAIT_V(n) asm volatile("s_waitcnt vmcnt(" #n ")" ::: "memory")
; #define PG8_WAIT_L(n) asm volatile("s_waitcnt lgkmcnt(" #n ")" ::: "memory")
; #define PG8_BAR __builtin_amdgcn_s_barrier()
; #define PG8_SCHED __builtin_amdgcn_sched_barrier(0)
; template <class Epi>
; __device__ __forceinline__ void gemm_phase(LAS unsigned char* lds, const Gemm g, const StaticOrder& S, const Epi& E) {
;     ...
;             PG8_LDB(B1, 0, 1); PG8_STAGE(PG8_SB(0, 0), b2, voffB);
;             PG8_BAR; PG8_WAIT_L(0); PG8_MMA(0, 1, At, B1); PG8_BAR;
;             PG8_LDA(At, 0, 1); PG8_STAGE(PG8_SA(0, 0), a2, voffA);
;             PG8_BAR; PG8_WAIT_L(0); PG8_MMA(1, 0, At, B0); PG8_BAR; PG8_SCHED;
;             PG8_STAGE(PG8_SB(0, 1), b2 + hstepB, voffB);
;             PG8_WAIT_V(6); PG8_BAR; PG8_MMA(1, 1, At, B1); PG8_BAR;
;             PG8_LDB(B0, 1, 0); PG8_SCHED; PG8_LDA(At, 1, 0); PG8_STAGE(PG8_SA(0, 1), a2 + hstepA, voffA);
;             PG8_WAIT_L(8); PG8_BAR; PG8_WAIT_L(0); PG8_MMA(0, 0, At, B0); PG8_BAR; PG8_SCHED;
	s_add_i32 s58, 0, 0x14000
	s_add_i32 s55, s55, s36
	v_add_u32_e32 v152, s58, v134
	v_lshl_add_u64 v[204:205], s[24:25], 0, v[128:129]
	s_mov_b32 m0, s55
	ds_read_b128 v[188:191], v152
	ds_read_b128 v[196:199], v152 offset:2048
	ds_read_b128 v[192:195], v152 offset:1024
	ds_read_b128 v[200:203], v152 offset:3072
	global_load_lds_dwordx4 v[204:205], off
	s_add_i32 m0, s55, 0x2000
	v_lshl_add_u64 v[204:205], s[24:25], 0, v[130:131]
	global_load_lds_dwordx4 v[204:205], off
	s_waitcnt lgkmcnt(0)
	s_barrier
	v_mfma_f32_16x16x32_bf16 v[116:119], v[188:191], v[156:159], v[116:119]
	s_setprio 1
	v_mfma_f32_16x16x32_bf16 v[112:115], v[196:199], v[156:159], v[112:115]
	s_mov_b32 m0, s37
	v_lshl_add_u64 v[204:205], s[28:29], 0, v[128:129]
	v_mfma_f32_16x16x32_bf16 v[100:103], v[188:191], v[164:167], v[100:103]
	v_mfma_f32_16x16x32_bf16 v[96:99], v[196:199], v[164:167], v[96:99]
	v_mfma_f32_16x16x32_bf16 v[84:87], v[188:191], v[172:175], v[84:87]
	v_mfma_f32_16x16x32_bf16 v[80:83], v[196:199], v[172:175], v[80:83]
	v_mfma_f32_16x16x32_bf16 v[68:71], v[188:191], v[180:183], v[68:71]
	v_mfma_f32_16x16x32_bf16 v[64:67], v[196:199], v[180:183], v[64:67]
	v_mfma_f32_16x16x32_bf16 v[116:119], v[192:195], v[160:163], v[116:119]
	v_mfma_f32_16x16x32_bf16 v[112:115], v[200:203], v[160:163], v[112:115]
	v_mfma_f32_16x16x32_bf16 v[100:103], v[192:195], v[168:171], v[100:103]
	v_mfma_f32_16x16x32_bf16 v[96:99], v[200:203], v[168:171], v[96:99]
	v_mfma_f32_16x16x32_bf16 v[84:87], v[192:195], v[176:179], v[84:87]
	v_mfma_f32_16x16x32_bf16 v[80:83], v[200:203], v[176:179], v[80:83]
	v_mfma_f32_16x16x32_bf16 v[68:71], v[192:195], v[184:187], v[68:71]
	s_setprio 0
	v_mfma_f32_16x16x32_bf16 v[64:67], v[200:203], v[184:187], v[64:67]
	s_barrier
	ds_read_b128 v[156:159], v135 offset:16384
	ds_read_b128 v[164:167], v135 offset:18432
	ds_read_b128 v[172:175], v135 offset:20480
	ds_read_b128 v[180:183], v135 offset:22528
	ds_read_b128 v[160:163], v135 offset:17408
	ds_read_b128 v[168:171], v135 offset:19456
	ds_read_b128 v[176:179], v135 offset:21504
	ds_read_b128 v[184:187], v135 offset:23552
	global_load_lds_dwordx4 v[204:205], off
	s_mov_b32 m0, s38
	v_lshl_add_u64 v[204:205], s[28:29], 0, v[130:131]
	global_load_lds_dwordx4 v[204:205], off
	s_add_u32 s56, s24, 0x80000
	s_addc_u32 s57, s25, 0
	s_add_i32 s55, s58, s36
	s_mov_b32 m0, s55
	v_lshl_add_u64 v[204:205], s[56:57], 0, v[128:129]
	global_load_lds_dwordx4 v[204:205], off
	s_add_i32 m0, s55, 0x2000
	v_lshl_add_u64 v[204:205], s[56:57], 0, v[130:131]
	global_load_lds_dwordx4 v[204:205], off
	s_waitcnt vmcnt(6)
	s_waitcnt lgkmcnt(0)
	s_barrier
	v_mfma_f32_16x16x32_bf16 v[60:63], v[136:139], v[156:159], v[60:63]
	s_setprio 1
	v_mfma_f32_16x16x32_bf16 v[56:59], v[144:147], v[156:159], v[56:59]
	v_mfma_f32_16x16x32_bf16 v[44:47], v[136:139], v[164:167], v[44:47]
	v_mfma_f32_16x16x32_bf16 v[40:43], v[144:147], v[164:167], v[40:43]
	v_mfma_f32_16x16x32_bf16 v[28:31], v[136:139], v[172:175], v[28:31]
	v_mfma_f32_16x16x32_bf16 v[24:27], v[144:147], v[172:175], v[24:27]
	v_mfma_f32_16x16x32_bf16 v[12:15], v[136:139], v[180:183], v[12:15]
	v_mfma_f32_16x16x32_bf16 v[8:11], v[144:147], v[180:183], v[8:11]
	v_mfma_f32_16x16x32_bf16 v[60:63], v[140:143], v[160:163], v[60:63]
	v_mfma_f32_16x16x32_bf16 v[56:59], v[148:151], v[160:163], v[56:59]
	v_mfma_f32_16x16x32_bf16 v[44:47], v[140:143], v[168:171], v[44:47]
	v_mfma_f32_16x16x32_bf16 v[40:43], v[148:151], v[168:171], v[40:43]
	v_mfma_f32_16x16x32_bf16 v[28:31], v[140:143], v[176:179], v[28:31]
	v_mfma_f32_16x16x32_bf16 v[24:27], v[148:151], v[176:179], v[24:27]
	v_mfma_f32_16x16x32_bf16 v[12:15], v[140:143], v[184:187], v[12:15]
	v_mfma_f32_16x16x32_bf16 v[8:11], v[148:151], v[184:187], v[8:11]
	v_mfma_f32_16x16x32_bf16 v[52:55], v[188:191], v[156:159], v[52:55]
	v_mfma_f32_16x16x32_bf16 v[48:51], v[196:199], v[156:159], v[48:51]
	s_add_i32 s55, 0, 0x18000
	v_add_u32_e32 v148, s55, v134
	v_mfma_f32_16x16x32_bf16 v[36:39], v[188:191], v[164:167], v[36:39]
	v_mfma_f32_16x16x32_bf16 v[32:35], v[196:199], v[164:167], v[32:35]
	v_mfma_f32_16x16x32_bf16 v[20:23], v[188:191], v[172:175], v[20:23]
	v_mfma_f32_16x16x32_bf16 v[16:19], v[196:199], v[172:175], v[16:19]
	v_mfma_f32_16x16x32_bf16 v[4:7], v[188:191], v[180:183], v[4:7]
	v_mfma_f32_16x16x32_bf16 v[0:3], v[196:199], v[180:183], v[0:3]
	v_mfma_f32_16x16x32_bf16 v[52:55], v[192:195], v[160:163], v[52:55]
	v_mfma_f32_16x16x32_bf16 v[48:51], v[200:203], v[160:163], v[48:51]
	v_mfma_f32_16x16x32_bf16 v[36:39], v[192:195], v[168:171], v[36:39]
	v_mfma_f32_16x16x32_bf16 v[32:35], v[200:203], v[168:171], v[32:35]
	v_mfma_f32_16x16x32_bf16 v[20:23], v[192:195], v[176:179], v[20:23]
	v_mfma_f32_16x16x32_bf16 v[16:19], v[200:203], v[176:179], v[16:19]
	v_mfma_f32_16x16x32_bf16 v[4:7], v[192:195], v[184:187], v[4:7]
	s_setprio 0
	v_mfma_f32_16x16x32_bf16 v[0:3], v[200:203], v[184:187], v[0:3]
	s_barrier
	ds_read_b128 v[136:139], v148
	ds_read_b128 v[144:147], v148 offset:2048
	ds_read_b128 v[140:143], v148 offset:1024
	ds_read_b128 v[148:151], v148 offset:3072
	s_add_u32 s28, s28, 0x80000
	s_addc_u32 s29, s29, 0
	s_mov_b32 m0, s39
	v_lshl_add_u64 v[188:189], s[28:29], 0, v[128:129]
	ds_read_b128 v[156:159], v135 offset:32768
	ds_read_b128 v[164:167], v135 offset:34816
	ds_read_b128 v[172:175], v135 offset:36864
	ds_read_b128 v[180:183], v135 offset:38912
	ds_read_b128 v[160:163], v135 offset:33792
	ds_read_b128 v[168:171], v135 offset:35840
	ds_read_b128 v[176:179], v135 offset:37888
	ds_read_b128 v[184:187], v135 offset:39936
	global_load_lds_dwordx4 v[188:189], off
	s_mov_b32 m0, s40
	v_lshl_add_u64 v[188:189], s[28:29], 0, v[130:131]
	global_load_lds_dwordx4 v[188:189], off
	s_waitcnt lgkmcnt(8)
	s_barrier
; #define PG8_STAGE(bufoff, gbase, voff) do { _Pragma("unroll") for (int _i = 0; _i < 2; ++_i) \
;         __builtin_amdgcn_global_load_lds((const unsigned*)((const char*)(gbase) + (voff)[_i]), (LAS unsigned*)(lds + (bufoff) + ldsw + _i * 8192), 16, 0, 0); } while (0)
; #define PG8_LDA(dst, b, h) do { _Pragma("unroll") for (int m = 0; m < 4; ++m) _Pragma("unroll") for (int k = 0; k < 2; ++k) dst[m][k] = *(const LAS bf16x8*)(lds + PG8_SA(b, h) + aoff + m * 2048 + k * 1024); } while (0)
; #define PG8_LDB(dst, b, h) do { _Pragma("unroll") for (int n = 0; n < 2; ++n) _Pragma("unroll") for (int k = 0; k < 2; ++k) dst[n][k] = *(const LAS bf16x8*)(lds + PG8_SB(b, h) + boff + n * 2048 + k * 1024); } while (0)
; #define PG8_MMA(ai, bj, At, Bt) do { __builtin_amdgcn_s_setprio(1); _Pragma("unroll") for (int m = 0; m < 4; ++m) _Pragma("unroll") for (int n = 0; n < 2; ++n) _Pragma("unroll") for (int k = 0; k < 2; ++k) \
;         acc[ai][bj][m][n] = __builtin_amdgcn_mfma_f32_16x16x32_bf16(Bt[n][k], At[m][k], acc[ai][bj][m][n], 0, 0, 0); __builtin_amdgcn_s_setprio(0); } while (0)
; #define PG8_WAIT_V(n) asm volatile("s_waitcnt vmcnt(" #n ")" ::: "memory")
; #define PG8_WAIT_L(n) asm volatile("s_waitcnt lgkmcnt(" #n ")" ::: "memory")
; #define PG8_BAR __builtin_amdgcn_s_barrier()
; #define PG8_SCHED __builtin_amdgcn_sched_barrier(0)
; template <class Epi>
; __device__ __forceinline__ void gemm_phase(LAS unsigned char* lds, const Gemm g, const StaticOrder& S, const Epi& E) {
;     ...
;             PG8_WAIT_L(8); PG8_BAR; PG8_WAIT_L(0); PG8_MMA(0, 0, At, B0); PG8_BAR; PG8_SCHED;
;             PG8_LDB(B1, 1, 1); PG8_STAGE(PG8_SB(1, 0), b3, voffB);
;             PG8_BAR; PG8_WAIT_L(0); PG8_MMA(0, 1, At, B1); PG8_BAR;
;             PG8_LDA(At, 1, 1); PG8_STAGE(PG8_SA(1, 0), a3, voffA);
;             PG8_BAR; PG8_WAIT_L(0); PG8_MMA(1, 0, At, B0); PG8_BAR; PG8_SCHED;
;             PG8_STAGE(PG8_SB(1, 1), b3 + hstepB, voffB);
;             PG8_WAIT_V(6); PG8_BAR; PG8_MMA(1, 1, At, B1); PG8_BAR;
	s_waitcnt lgkmcnt(7)
	v_mfma_f32_16x16x32_bf16 v[124:127], v[136:139], v[156:159], v[124:127]
	s_setprio 1
	v_mfma_f32_16x16x32_bf16 v[120:123], v[144:147], v[156:159], v[120:123]
	s_waitcnt lgkmcnt(6)
	v_mfma_f32_16x16x32_bf16 v[108:111], v[136:139], v[164:167], v[108:111]
	v_mfma_f32_16x16x32_bf16 v[104:107], v[144:147], v[164:167], v[104:107]
	s_waitcnt lgkmcnt(5)
	v_mfma_f32_16x16x32_bf16 v[92:95], v[136:139], v[172:175], v[92:95]
	v_mfma_f32_16x16x32_bf16 v[88:91], v[144:147], v[172:175], v[88:91]
	s_waitcnt lgkmcnt(4)
	v_mfma_f32_16x16x32_bf16 v[76:79], v[136:139], v[180:183], v[76:79]
	v_mfma_f32_16x16x32_bf16 v[72:75], v[144:147], v[180:183], v[72:75]
	s_waitcnt lgkmcnt(3)
	v_mfma_f32_16x16x32_bf16 v[124:127], v[140:143], v[160:163], v[124:127]
	v_mfma_f32_16x16x32_bf16 v[120:123], v[148:151], v[160:163], v[120:123]
	s_waitcnt lgkmcnt(2)
	v_mfma_f32_16x16x32_bf16 v[108:111], v[140:143], v[168:171], v[108:111]
	v_mfma_f32_16x16x32_bf16 v[104:107], v[148:151], v[168:171], v[104:107]
	s_waitcnt lgkmcnt(1)
	v_mfma_f32_16x16x32_bf16 v[92:95], v[140:143], v[176:179], v[92:95]
	v_mfma_f32_16x16x32_bf16 v[88:91], v[148:151], v[176:179], v[88:91]
	s_waitcnt lgkmcnt(0)
	v_mfma_f32_16x16x32_bf16 v[76:79], v[140:143], v[184:187], v[76:79]
	s_setprio 0
	v_mfma_f32_16x16x32_bf16 v[72:75], v[148:151], v[184:187], v[72:75]
	s_barrier
	s_add_i32 s56, 0, 0x1c000
	s_add_u32 s28, s24, 0x4000
	s_addc_u32 s29, s25, 0
	s_add_i32 s55, s55, s36
	v_add_u32_e32 v152, s56, v134
	v_lshl_add_u64 v[204:205], s[28:29], 0, v[128:129]
	s_mov_b32 m0, s55
	ds_read_b128 v[188:191], v152
	ds_read_b128 v[196:199], v152 offset:2048
	ds_read_b128 v[192:195], v152 offset:1024
	ds_read_b128 v[200:203], v152 offset:3072
	global_load_lds_dwordx4 v[204:205], off
	s_add_i32 m0, s55, 0x2000
	v_lshl_add_u64 v[204:205], s[28:29], 0, v[130:131]
	global_load_lds_dwordx4 v[204:205], off
	s_waitcnt lgkmcnt(0)
	s_barrier
	v_mfma_f32_16x16x32_bf16 v[116:119], v[188:191], v[156:159], v[116:119]
	s_setprio 1
	v_mfma_f32_16x16x32_bf16 v[112:115], v[196:199], v[156:159], v[112:115]
	s_mov_b32 m0, s43
	v_lshl_add_u64 v[204:205], s[26:27], 0, v[128:129]
	v_mfma_f32_16x16x32_bf16 v[100:103], v[188:191], v[164:167], v[100:103]
	v_mfma_f32_16x16x32_bf16 v[96:99], v[196:199], v[164:167], v[96:99]
	v_mfma_f32_16x16x32_bf16 v[84:87], v[188:191], v[172:175], v[84:87]
	v_mfma_f32_16x16x32_bf16 v[80:83], v[196:199], v[172:175], v[80:83]
	v_mfma_f32_16x16x32_bf16 v[68:71], v[188:191], v[180:183], v[68:71]
	v_mfma_f32_16x16x32_bf16 v[64:67], v[196:199], v[180:183], v[64:67]
	v_mfma_f32_16x16x32_bf16 v[116:119], v[192:195], v[160:163], v[116:119]
	v_mfma_f32_16x16x32_bf16 v[112:115], v[200:203], v[160:163], v[112:115]
	v_mfma_f32_16x16x32_bf16 v[100:103], v[192:195], v[168:171], v[100:103]
	v_mfma_f32_16x16x32_bf16 v[96:99], v[200:203], v[168:171], v[96:99]
	v_mfma_f32_16x16x32_bf16 v[84:87], v[192:195], v[176:179], v[84:87]
	v_mfma_f32_16x16x32_bf16 v[80:83], v[200:203], v[176:179], v[80:83]
	v_mfma_f32_16x16x32_bf16 v[68:71], v[192:195], v[184:187], v[68:71]
	s_setprio 0
	v_mfma_f32_16x16x32_bf16 v[64:67], v[200:203], v[184:187], v[64:67]
	s_barrier
	ds_read_b128 v[156:159], v135 offset:49152
	ds_read_b128 v[164:167], v135 offset:51200
	ds_read_b128 v[172:175], v135 offset:53248
	ds_read_b128 v[180:183], v135 offset:55296
	ds_read_b128 v[160:163], v135 offset:50176
	ds_read_b128 v[168:171], v135 offset:52224
	ds_read_b128 v[176:179], v135 offset:54272
	ds_read_b128 v[184:187], v135 offset:56320
	global_load_lds_dwordx4 v[204:205], off
	s_mov_b32 m0, s44
	v_lshl_add_u64 v[204:205], s[26:27], 0, v[130:131]
	global_load_lds_dwordx4 v[204:205], off
	s_add_u32 s24, s24, 0x84000
	s_addc_u32 s25, s25, 0
	s_add_i32 s26, s56, s36
	s_mov_b32 m0, s26
	v_lshl_add_u64 v[204:205], s[24:25], 0, v[128:129]
	global_load_lds_dwordx4 v[204:205], off
	s_add_i32 m0, s26, 0x2000
	v_lshl_add_u64 v[204:205], s[24:25], 0, v[130:131]
	global_load_lds_dwordx4 v[204:205], off
	s_waitcnt vmcnt(6)
	s_waitcnt lgkmcnt(0)
	s_barrier
	v_mfma_f32_16x16x32_bf16 v[60:63], v[136:139], v[156:159], v[60:63]
	s_setprio 1
	v_mfma_f32_16x16x32_bf16 v[56:59], v[144:147], v[156:159], v[56:59]
	v_mfma_f32_16x16x32_bf16 v[44:47], v[136:139], v[164:167], v[44:47]
	v_mfma_f32_16x16x32_bf16 v[40:43], v[144:147], v[164:167], v[40:43]
	v_mfma_f32_16x16x32_bf16 v[28:31], v[136:139], v[172:175], v[28:31]
	v_mfma_f32_16x16x32_bf16 v[24:27], v[144:147], v[172:175], v[24:27]
	v_mfma_f32_16x16x32_bf16 v[12:15], v[136:139], v[180:183], v[12:15]
	v_mfma_f32_16x16x32_bf16 v[8:11], v[144:147], v[180:183], v[8:11]
	v_mfma_f32_16x16x32_bf16 v[60:63], v[140:143], v[160:163], v[60:63]
	v_mfma_f32_16x16x32_bf16 v[56:59], v[148:151], v[160:163], v[56:59]
	v_mfma_f32_16x16x32_bf16 v[44:47], v[140:143], v[168:171], v[44:47]
	v_mfma_f32_16x16x32_bf16 v[40:43], v[148:151], v[168:171], v[40:43]
	v_mfma_f32_16x16x32_bf16 v[28:31], v[140:143], v[176:179], v[28:31]
	v_mfma_f32_16x16x32_bf16 v[24:27], v[148:151], v[176:179], v[24:27]
	v_mfma_f32_16x16x32_bf16 v[12:15], v[140:143], v[184:187], v[12:15]
	v_mfma_f32_16x16x32_bf16 v[8:11], v[148:151], v[184:187], v[8:11]
	v_mfma_f32_16x16x32_bf16 v[52:55], v[188:191], v[156:159], v[52:55]
	v_mfma_f32_16x16x32_bf16 v[48:51], v[196:199], v[156:159], v[48:51]
	s_add_i32 s54, s54, 2
	s_add_u32 s22, s22, 0x8000
	s_addc_u32 s23, s23, 0
	s_add_u32 s51, s51, 0x8000
	s_addc_u32 s52, s52, 0
	v_mfma_f32_16x16x32_bf16 v[36:39], v[188:191], v[164:167], v[36:39]
	v_mfma_f32_16x16x32_bf16 v[32:35], v[196:199], v[164:167], v[32:35]
	v_mfma_f32_16x16x32_bf16 v[20:23], v[188:191], v[172:175], v[20:23]
	v_mfma_f32_16x16x32_bf16 v[16:19], v[196:199], v[172:175], v[16:19]
	v_mfma_f32_16x16x32_bf16 v[4:7], v[188:191], v[180:183], v[4:7]
	v_mfma_f32_16x16x32_bf16 v[0:3], v[196:199], v[180:183], v[0:3]
	v_mfma_f32_16x16x32_bf16 v[52:55], v[192:195], v[160:163], v[52:55]
	v_mfma_f32_16x16x32_bf16 v[48:51], v[200:203], v[160:163], v[48:51]
	v_mfma_f32_16x16x32_bf16 v[36:39], v[192:195], v[168:171], v[36:39]
	v_mfma_f32_16x16x32_bf16 v[32:35], v[200:203], v[168:171], v[32:35]
	v_mfma_f32_16x16x32_bf16 v[20:23], v[192:195], v[176:179], v[20:23]
	v_mfma_f32_16x16x32_bf16 v[16:19], v[200:203], v[176:179], v[16:19]
	v_mfma_f32_16x16x32_bf16 v[4:7], v[192:195], v[184:187], v[4:7]
	s_cmp_gt_u32 s54, 29
	s_setprio 0
	v_mfma_f32_16x16x32_bf16 v[0:3], v[200:203], v[184:187], v[0:3]
	s_barrier
	s_cbranch_scc0 .LBB0_141

; #define PG8_STAGE(bufoff, gbase, voff) do { _Pragma("unroll") for (int _i = 0; _i < 2; ++_i) \
;         __builtin_amdgcn_global_load_lds((const unsigned*)((const char*)(gbase) + (voff)[_i]), (LAS unsigned*)(lds + (bufoff) + ldsw + _i * 8192), 16, 0, 0); } while (0)
; #define PG8_LDA(dst, b, h) do { _Pragma("unroll") for (int m = 0; m < 4; ++m) _Pragma("unroll") for (int k = 0; k < 2; ++k) dst[m][k] = *(const LAS bf16x8*)(lds + PG8_SA(b, h) + aoff + m * 2048 + k * 1024); } while (0)
; #define PG8_LDB(dst, b, h) do { _Pragma("unroll") for (int n = 0; n < 2; ++n) _Pragma("unroll") for (int k = 0; k < 2; ++k) dst[n][k] = *(const LAS bf16x8*)(lds + PG8_SB(b, h) + boff + n * 2048 + k * 1024); } while (0)
; #define PG8_MMA(ai, bj, At, Bt) do { __builtin_amdgcn_s_setprio(1); _Pragma("unroll") for (int m = 0; m < 4; ++m) _Pragma("unroll") for (int n = 0; n < 2; ++n) _Pragma("unroll") for (int k = 0; k < 2; ++k) \
;         acc[ai][bj][m][n] = __builtin_amdgcn_mfma_f32_16x16x32_bf16(Bt[n][k], At[m][k], acc[ai][bj][m][n], 0, 0, 0); __builtin_amdgcn_s_setprio(0); } while (0)
; template <class Epi>
; __device__ __forceinline__ void gemm_phase(LAS unsigned char* lds, const Gemm g, const StaticOrder& S, const Epi& E) {
;     ...
;         const char* nA = has_next ? (const char*)g.A + (size_t)nxt.pm * tstepA : cA; const char* nB = has_next ? (const char*)g.Bt + (size_t)nxt.pn * tstepB : cB;
;         for (int t = 0; t < nt; t += 2) {
;             const bool last = (t == nt - 2);
;             const char* a1 = cA + (size_t)(t + 1) * kstep;
;             const char* a2 = last ? nA : cA + (size_t)(t + 2) * kstep; const char* b2 = last ? nB : cB + (size_t)(t + 2) * kstep;
;             const char* a3 = a2 + kstep; const char* b3 = b2 + kstep;
;             PG8_LDB(B0, 0, 0); PG8_SCHED; PG8_LDA(At, 0, 0); PG8_STAGE(PG8_SA(1, 1), a1 + hstepA, voffA);
;             PG8_WAIT_L(8); PG8_BAR; PG8_WAIT_L(0); PG8_MMA(0, 0, At, B0); PG8_BAR; PG8_SCHED;
;             PG8_LDB(B1, 0, 1); PG8_STAGE(PG8_SB(0, 0), b2, voffB);
;             PG8_BAR; PG8_WAIT_L(0); PG8_MMA(0, 1, At, B1); PG8_BAR;
;             PG8_LDA(At, 0, 1); PG8_STAGE(PG8_SA(0, 0), a2, voffA);
;             PG8_BAR; PG8_WAIT_L(0); PG8_MMA(1, 0, At, B0); PG8_BAR; PG8_SCHED;
;             PG8_STAGE(PG8_SB(0, 1), b2 + hstepB, voffB);
;             PG8_WAIT_V(6); PG8_BAR; PG8_MMA(1, 1, At, B1); PG8_BAR;
.LBB0_186:
	s_add_u32 s4, s24, 0x4000
	s_addc_u32 s5, s25, 0
	s_add_u32 s50, s22, 0x8000
	s_addc_u32 s51, s23, 0
	s_mov_b32 s22, 0
	s_add_i32 s54, s22, 2
	s_add_u32 s23, s4, 0x4000
	s_addc_u32 s24, s5, 0
	s_cmp_eq_u32 s40, s22
	s_cselect_b32 s26, s6, s23
	s_cselect_b32 s27, s7, s24
	s_cselect_b32 s24, s20, s50
	s_cselect_b32 s25, s21, s51
	s_add_u32 s22, s26, 0x4000
	s_addc_u32 s23, s27, 0
	s_add_i32 s55, 0, 0x10000
	v_add_u32_e32 v140, s55, v207
	ds_read_b128 v[128:131], v140
	ds_read_b128 v[136:139], v140 offset:2048
	ds_read_b128 v[132:135], v140 offset:1024
	ds_read_b128 v[140:143], v140 offset:3072
	v_lshl_add_u64 v[186:187], s[4:5], 0, v[158:159]
	s_add_i32 m0, s33, 0xc000
	ds_read_b128 v[144:147], v209
	ds_read_b128 v[162:165], v209 offset:2048
	ds_read_b128 v[170:173], v209 offset:4096
	ds_read_b128 v[178:181], v209 offset:6144
	ds_read_b128 v[148:151], v209 offset:1024
	ds_read_b128 v[166:169], v209 offset:3072
	ds_read_b128 v[174:177], v209 offset:5120
	ds_read_b128 v[182:185], v209 offset:7168
	global_load_lds_dwordx4 v[186:187], off
	s_add_i32 m0, s33, 0xe000
	v_lshl_add_u64 v[186:187], s[4:5], 0, v[160:161]
	global_load_lds_dwordx4 v[186:187], off
	s_waitcnt lgkmcnt(8)
	s_barrier
	s_waitcnt lgkmcnt(7)
	v_mfma_f32_16x16x32_bf16 v[124:127], v[128:131], v[144:147], 0
	s_setprio 1
	v_mfma_f32_16x16x32_bf16 v[120:123], v[136:139], v[144:147], 0
	s_waitcnt lgkmcnt(6)
	v_mfma_f32_16x16x32_bf16 v[116:119], v[128:131], v[162:165], 0
	v_mfma_f32_16x16x32_bf16 v[112:115], v[136:139], v[162:165], 0
	s_waitcnt lgkmcnt(5)
	v_mfma_f32_16x16x32_bf16 v[108:111], v[128:131], v[170:173], 0
	v_mfma_f32_16x16x32_bf16 v[104:107], v[136:139], v[170:173], 0
	s_waitcnt lgkmcnt(4)
	v_mfma_f32_16x16x32_bf16 v[100:103], v[128:131], v[178:181], 0
	v_mfma_f32_16x16x32_bf16 v[96:99], v[136:139], v[178:181], 0
	s_waitcnt lgkmcnt(3)
	v_mfma_f32_16x16x32_bf16 v[124:127], v[132:135], v[148:151], v[124:127]
	v_mfma_f32_16x16x32_bf16 v[120:123], v[140:143], v[148:151], v[120:123]
	s_waitcnt lgkmcnt(2)
	v_mfma_f32_16x16x32_bf16 v[116:119], v[132:135], v[166:169], v[116:119]
	v_mfma_f32_16x16x32_bf16 v[112:115], v[140:143], v[166:169], v[112:115]
	s_waitcnt lgkmcnt(1)
	v_mfma_f32_16x16x32_bf16 v[108:111], v[132:135], v[174:177], v[108:111]
	v_mfma_f32_16x16x32_bf16 v[104:107], v[140:143], v[174:177], v[104:107]
	s_waitcnt lgkmcnt(0)
	v_mfma_f32_16x16x32_bf16 v[100:103], v[132:135], v[182:185], v[100:103]
	s_setprio 0
	v_mfma_f32_16x16x32_bf16 v[96:99], v[140:143], v[182:185], v[96:99]
	s_barrier
	s_add_i32 s58, 0, 0x14000
	s_add_i32 s55, s55, s31
	v_add_u32_e32 v198, s58, v207
	v_lshl_add_u64 v[202:203], s[24:25], 0, v[152:153]
	s_mov_b32 m0, s55
	ds_read_b128 v[186:189], v198
	ds_read_b128 v[194:197], v198 offset:2048
	ds_read_b128 v[190:193], v198 offset:1024
	ds_read_b128 v[198:201], v198 offset:3072
	global_load_lds_dwordx4 v[202:203], off
	s_add_i32 m0, s55, 0x2000
	v_lshl_add_u64 v[202:203], s[24:25], 0, v[156:157]
	global_load_lds_dwordx4 v[202:203], off
	s_waitcnt lgkmcnt(0)
	s_barrier
	v_mfma_f32_16x16x32_bf16 v[92:95], v[186:189], v[144:147], 0
	s_setprio 1
	v_mfma_f32_16x16x32_bf16 v[88:91], v[194:197], v[144:147], 0
	s_mov_b32 m0, s33
	v_lshl_add_u64 v[202:203], s[26:27], 0, v[152:153]
	v_mfma_f32_16x16x32_bf16 v[84:87], v[186:189], v[162:165], 0
	v_mfma_f32_16x16x32_bf16 v[80:83], v[194:197], v[162:165], 0
	v_mfma_f32_16x16x32_bf16 v[76:79], v[186:189], v[170:173], 0
	v_mfma_f32_16x16x32_bf16 v[72:75], v[194:197], v[170:173], 0
	v_mfma_f32_16x16x32_bf16 v[68:71], v[186:189], v[178:181], 0
	v_mfma_f32_16x16x32_bf16 v[64:67], v[194:197], v[178:181], 0
	v_mfma_f32_16x16x32_bf16 v[92:95], v[190:193], v[148:151], v[92:95]
	v_mfma_f32_16x16x32_bf16 v[88:91], v[198:201], v[148:151], v[88:91]
	v_mfma_f32_16x16x32_bf16 v[84:87], v[190:193], v[166:169], v[84:87]
	v_mfma_f32_16x16x32_bf16 v[80:83], v[198:201], v[166:169], v[80:83]
	v_mfma_f32_16x16x32_bf16 v[76:79], v[190:193], v[174:177], v[76:79]
	v_mfma_f32_16x16x32_bf16 v[72:75], v[198:201], v[174:177], v[72:75]
	v_mfma_f32_16x16x32_bf16 v[68:71], v[190:193], v[182:185], v[68:71]
	s_setprio 0
	v_mfma_f32_16x16x32_bf16 v[64:67], v[198:201], v[182:185], v[64:67]
	s_barrier
	ds_read_b128 v[144:147], v209 offset:16384
	ds_read_b128 v[162:165], v209 offset:18432
	ds_read_b128 v[170:173], v209 offset:20480
	ds_read_b128 v[178:181], v209 offset:22528
	ds_read_b128 v[148:151], v209 offset:17408
	ds_read_b128 v[166:169], v209 offset:19456
	ds_read_b128 v[174:177], v209 offset:21504
	ds_read_b128 v[182:185], v209 offset:23552
	global_load_lds_dwordx4 v[202:203], off
	s_mov_b32 m0, s34
	v_lshl_add_u64 v[202:203], s[26:27], 0, v[156:157]
	global_load_lds_dwordx4 v[202:203], off
	s_add_u32 s56, s24, s52
	s_addc_u32 s57, s25, 0
	s_add_i32 s55, s58, s31
	s_mov_b32 m0, s55
	v_lshl_add_u64 v[202:203], s[56:57], 0, v[152:153]
	global_load_lds_dwordx4 v[202:203], off
	s_add_i32 m0, s55, 0x2000
	v_lshl_add_u64 v[202:203], s[56:57], 0, v[156:157]
	global_load_lds_dwordx4 v[202:203], off
	s_waitcnt vmcnt(6)
	s_waitcnt lgkmcnt(0)
	s_barrier
; #define PG8_STAGE(bufoff, gbase, voff) do { _Pragma("unroll") for (int _i = 0; _i < 2; ++_i) \
;         __builtin_amdgcn_global_load_lds((const unsigned*)((const char*)(gbase) + (voff)[_i]), (LAS unsigned*)(lds + (bufoff) + ldsw + _i * 8192), 16, 0, 0); } while (0)
; #define PG8_LDA(dst, b, h) do { _Pragma("unroll") for (int m = 0; m < 4; ++m) _Pragma("unroll") for (int k = 0; k < 2; ++k) dst[m][k] = *(const LAS bf16x8*)(lds + PG8_SA(b, h) + aoff + m * 2048 + k * 1024); } while (0)
; #define PG8_LDB(dst, b, h) do { _Pragma("unroll") for (int n = 0; n < 2; ++n) _Pragma("unroll") for (int k = 0; k < 2; ++k) dst[n][k] = *(const LAS bf16x8*)(lds + PG8_SB(b, h) + boff + n * 2048 + k * 1024); } while (0)
; #define PG8_MMA(ai, bj, At, Bt) do { __builtin_amdgcn_s_setprio(1); _Pragma("unroll") for (int m = 0; m < 4; ++m) _Pragma("unroll") for (int n = 0; n < 2; ++n) _Pragma("unroll") for (int k = 0; k < 2; ++k) \
;         acc[ai][bj][m][n] = __builtin_amdgcn_mfma_f32_16x16x32_bf16(Bt[n][k], At[m][k], acc[ai][bj][m][n], 0, 0, 0); __builtin_amdgcn_s_setprio(0); } while (0)
; #define PG8_WAIT_V(n) asm volatile("s_waitcnt vmcnt(" #n ")" ::: "memory")
; #define PG8_WAIT_L(n) asm volatile("s_waitcnt lgkmcnt(" #n ")" ::: "memory")
; #define PG8_BAR __builtin_amdgcn_s_barrier()
; #define PG8_SCHED __builtin_amdgcn_sched_barrier(0)
; template <class Epi>
; __device__ __forceinline__ void gemm_phase(LAS unsigned char* lds, const Gemm g, const StaticOrder& S, const Epi& E) {
;     ...
;             PG8_BAR; PG8_WAIT_L(0); PG8_MMA(1, 0, At, B0); PG8_BAR; PG8_SCHED;
;             PG8_STAGE(PG8_SB(0, 1), b2 + hstepB, voffB);
;             PG8_WAIT_V(6); PG8_BAR; PG8_MMA(1, 1, At, B1); PG8_BAR;
;             PG8_LDB(B0, 1, 0); PG8_SCHED; PG8_LDA(At, 1, 0); PG8_STAGE(PG8_SA(0, 1), a2 + hstepA, voffA);
;             PG8_WAIT_L(8); PG8_BAR; PG8_WAIT_L(0); PG8_MMA(0, 0, At, B0); PG8_BAR; PG8_SCHED;
;             PG8_LDB(B1, 1, 1); PG8_STAGE(PG8_SB(1, 0), b3, voffB);
;             PG8_BAR; PG8_WAIT_L(0); PG8_MMA(0, 1, At, B1); PG8_BAR;
	v_mfma_f32_16x16x32_bf16 v[60:63], v[128:131], v[144:147], 0
	s_setprio 1
	v_mfma_f32_16x16x32_bf16 v[56:59], v[136:139], v[144:147], 0
	v_mfma_f32_16x16x32_bf16 v[52:55], v[128:131], v[162:165], 0
	v_mfma_f32_16x16x32_bf16 v[48:51], v[136:139], v[162:165], 0
	v_mfma_f32_16x16x32_bf16 v[44:47], v[128:131], v[170:173], 0
	v_mfma_f32_16x16x32_bf16 v[40:43], v[136:139], v[170:173], 0
	v_mfma_f32_16x16x32_bf16 v[36:39], v[128:131], v[178:181], 0
	v_mfma_f32_16x16x32_bf16 v[32:35], v[136:139], v[178:181], 0
	v_mfma_f32_16x16x32_bf16 v[60:63], v[132:135], v[148:151], v[60:63]
	v_mfma_f32_16x16x32_bf16 v[56:59], v[140:143], v[148:151], v[56:59]
	v_mfma_f32_16x16x32_bf16 v[52:55], v[132:135], v[166:169], v[52:55]
	v_mfma_f32_16x16x32_bf16 v[48:51], v[140:143], v[166:169], v[48:51]
	v_mfma_f32_16x16x32_bf16 v[44:47], v[132:135], v[174:177], v[44:47]
	v_mfma_f32_16x16x32_bf16 v[40:43], v[140:143], v[174:177], v[40:43]
	v_mfma_f32_16x16x32_bf16 v[36:39], v[132:135], v[182:185], v[36:39]
	v_mfma_f32_16x16x32_bf16 v[32:35], v[140:143], v[182:185], v[32:35]
	v_mfma_f32_16x16x32_bf16 v[28:31], v[186:189], v[144:147], 0
	v_mfma_f32_16x16x32_bf16 v[24:27], v[194:197], v[144:147], 0
	s_add_i32 s55, 0, 0x18000
	v_add_u32_e32 v140, s55, v207
	v_mfma_f32_16x16x32_bf16 v[20:23], v[186:189], v[162:165], 0
	v_mfma_f32_16x16x32_bf16 v[16:19], v[194:197], v[162:165], 0
	v_mfma_f32_16x16x32_bf16 v[12:15], v[186:189], v[170:173], 0
	v_mfma_f32_16x16x32_bf16 v[8:11], v[194:197], v[170:173], 0
	v_mfma_f32_16x16x32_bf16 v[4:7], v[186:189], v[178:181], 0
	v_mfma_f32_16x16x32_bf16 v[0:3], v[194:197], v[178:181], 0
	v_mfma_f32_16x16x32_bf16 v[28:31], v[190:193], v[148:151], v[28:31]
	v_mfma_f32_16x16x32_bf16 v[24:27], v[198:201], v[148:151], v[24:27]
	v_mfma_f32_16x16x32_bf16 v[20:23], v[190:193], v[166:169], v[20:23]
	v_mfma_f32_16x16x32_bf16 v[16:19], v[198:201], v[166:169], v[16:19]
	v_mfma_f32_16x16x32_bf16 v[12:15], v[190:193], v[174:177], v[12:15]
	v_mfma_f32_16x16x32_bf16 v[8:11], v[198:201], v[174:177], v[8:11]
	v_mfma_f32_16x16x32_bf16 v[4:7], v[190:193], v[182:185], v[4:7]
	s_setprio 0
	v_mfma_f32_16x16x32_bf16 v[0:3], v[198:201], v[182:185], v[0:3]
	s_barrier
	ds_read_b128 v[128:131], v140
	ds_read_b128 v[136:139], v140 offset:2048
	ds_read_b128 v[132:135], v140 offset:1024
	ds_read_b128 v[140:143], v140 offset:3072
	s_add_u32 s26, s26, s52
	s_addc_u32 s27, s27, 0
	s_mov_b32 m0, s35
	v_lshl_add_u64 v[186:187], s[26:27], 0, v[152:153]
	ds_read_b128 v[144:147], v209 offset:32768
	ds_read_b128 v[162:165], v209 offset:34816
	ds_read_b128 v[170:173], v209 offset:36864
	ds_read_b128 v[178:181], v209 offset:38912
	ds_read_b128 v[148:151], v209 offset:33792
	ds_read_b128 v[166:169], v209 offset:35840
	ds_read_b128 v[174:177], v209 offset:37888
	ds_read_b128 v[182:185], v209 offset:39936
	global_load_lds_dwordx4 v[186:187], off
	s_mov_b32 m0, s36
	v_lshl_add_u64 v[186:187], s[26:27], 0, v[156:157]
	global_load_lds_dwordx4 v[186:187], off
	s_waitcnt lgkmcnt(8)
	s_barrier
	s_waitcnt lgkmcnt(7)
	v_mfma_f32_16x16x32_bf16 v[124:127], v[128:131], v[144:147], v[124:127]
	s_setprio 1
	v_mfma_f32_16x16x32_bf16 v[120:123], v[136:139], v[144:147], v[120:123]
	s_waitcnt lgkmcnt(6)
	v_mfma_f32_16x16x32_bf16 v[116:119], v[128:131], v[162:165], v[116:119]
	v_mfma_f32_16x16x32_bf16 v[112:115], v[136:139], v[162:165], v[112:115]
	s_waitcnt lgkmcnt(5)
	v_mfma_f32_16x16x32_bf16 v[108:111], v[128:131], v[170:173], v[108:111]
	v_mfma_f32_16x16x32_bf16 v[104:107], v[136:139], v[170:173], v[104:107]
	s_waitcnt lgkmcnt(4)
	v_mfma_f32_16x16x32_bf16 v[100:103], v[128:131], v[178:181], v[100:103]
	v_mfma_f32_16x16x32_bf16 v[96:99], v[136:139], v[178:181], v[96:99]
	s_waitcnt lgkmcnt(3)
	v_mfma_f32_16x16x32_bf16 v[124:127], v[132:135], v[148:151], v[124:127]
	v_mfma_f32_16x16x32_bf16 v[120:123], v[140:143], v[148:151], v[120:123]
	s_waitcnt lgkmcnt(2)
	v_mfma_f32_16x16x32_bf16 v[116:119], v[132:135], v[166:169], v[116:119]
	v_mfma_f32_16x16x32_bf16 v[112:115], v[140:143], v[166:169], v[112:115]
	s_waitcnt lgkmcnt(1)
	v_mfma_f32_16x16x32_bf16 v[108:111], v[132:135], v[174:177], v[108:111]
	v_mfma_f32_16x16x32_bf16 v[104:107], v[140:143], v[174:177], v[104:107]
	s_waitcnt lgkmcnt(0)
	v_mfma_f32_16x16x32_bf16 v[100:103], v[132:135], v[182:185], v[100:103]
	s_setprio 0
	v_mfma_f32_16x16x32_bf16 v[96:99], v[140:143], v[182:185], v[96:99]
	s_barrier
	s_add_i32 s26, 0, 0x1c000
	s_add_u32 s24, s24, 0x4000
	s_addc_u32 s25, s25, 0
	s_add_i32 s27, s55, s31
	v_add_u32_e32 v198, s26, v207
	v_lshl_add_u64 v[202:203], s[24:25], 0, v[152:153]
	s_mov_b32 m0, s27
	ds_read_b128 v[186:189], v198
	ds_read_b128 v[194:197], v198 offset:2048
	ds_read_b128 v[190:193], v198 offset:1024
	ds_read_b128 v[198:201], v198 offset:3072
	global_load_lds_dwordx4 v[202:203], off
	s_add_i32 m0, s27, 0x2000
	v_lshl_add_u64 v[202:203], s[24:25], 0, v[156:157]
	global_load_lds_dwordx4 v[202:203], off
	s_waitcnt lgkmcnt(0)
	s_barrier
	v_mfma_f32_16x16x32_bf16 v[92:95], v[186:189], v[144:147], v[92:95]
	s_setprio 1
	v_mfma_f32_16x16x32_bf16 v[88:91], v[194:197], v[144:147], v[88:91]
	s_mov_b32 m0, s38
	v_lshl_add_u64 v[202:203], s[22:23], 0, v[152:153]
	v_mfma_f32_16x16x32_bf16 v[84:87], v[186:189], v[162:165], v[84:87]
	v_mfma_f32_16x16x32_bf16 v[80:83], v[194:197], v[162:165], v[80:83]
	v_mfma_f32_16x16x32_bf16 v[76:79], v[186:189], v[170:173], v[76:79]
	v_mfma_f32_16x16x32_bf16 v[72:75], v[194:197], v[170:173], v[72:75]
	v_mfma_f32_16x16x32_bf16 v[68:71], v[186:189], v[178:181], v[68:71]
	v_mfma_f32_16x16x32_bf16 v[64:67], v[194:197], v[178:181], v[64:67]
	v_mfma_f32_16x16x32_bf16 v[92:95], v[190:193], v[148:151], v[92:95]
	v_mfma_f32_16x16x32_bf16 v[88:91], v[198:201], v[148:151], v[88:91]
	v_mfma_f32_16x16x32_bf16 v[84:87], v[190:193], v[166:169], v[84:87]
	v_mfma_f32_16x16x32_bf16 v[80:83], v[198:201], v[166:169], v[80:83]
	v_mfma_f32_16x16x32_bf16 v[76:79], v[190:193], v[174:177], v[76:79]
	v_mfma_f32_16x16x32_bf16 v[72:75], v[198:201], v[174:177], v[72:75]
	v_mfma_f32_16x16x32_bf16 v[68:71], v[190:193], v[182:185], v[68:71]
	s_setprio 0
	v_mfma_f32_16x16x32_bf16 v[64:67], v[198:201], v[182:185], v[64:67]
	s_barrier
; #define PG8_STAGE(bufoff, gbase, voff) do { _Pragma("unroll") for (int _i = 0; _i < 2; ++_i) \
;         __builtin_amdgcn_global_load_lds((const unsigned*)((const char*)(gbase) + (voff)[_i]), (LAS unsigned*)(lds + (bufoff) + ldsw + _i * 8192), 16, 0, 0); } while (0)
; #define PG8_LDA(dst, b, h) do { _Pragma("unroll") for (int m = 0; m < 4; ++m) _Pragma("unroll") for (int k = 0; k < 2; ++k) dst[m][k] = *(const LAS bf16x8*)(lds + PG8_SA(b, h) + aoff + m * 2048 + k * 1024); } while (0)
; #define PG8_WAIT_V(n) asm volatile("s_waitcnt vmcnt(" #n ")" ::: "memory")
; #define PG8_WAIT_L(n) asm volatile("s_waitcnt lgkmcnt(" #n ")" ::: "memory")
; #define PG8_BAR __builtin_amdgcn_s_barrier()
; template <class Epi>
; __device__ __forceinline__ void gemm_phase(LAS unsigned char* lds, const Gemm g, const StaticOrder& S, const Epi& E) {
;     ...
;             const bool last = (t == nt - 2);
;             const char* a1 = cA + (size_t)(t + 1) * kstep;
;             const char* a2 = last ? nA : cA + (size_t)(t + 2) * kstep; const char* b2 = last ? nB : cB + (size_t)(t + 2) * kstep;
;             const char* a3 = a2 + kstep; const char* b3 = b2 + kstep;
;             PG8_LDB(B0, 0, 0); PG8_SCHED; PG8_LDA(At, 0, 0); PG8_STAGE(PG8_SA(1, 1), a1 + hstepA, voffA);
;             PG8_WAIT_L(8); PG8_BAR; PG8_WAIT_L(0); PG8_MMA(0, 0, At, B0); PG8_BAR; PG8_SCHED;
;             PG8_LDB(B1, 0, 1); PG8_STAGE(PG8_SB(0, 0), b2, voffB);
;             PG8_BAR; PG8_WAIT_L(0); PG8_MMA(0, 1, At, B1); PG8_BAR;
;             PG8_LDA(At, 0, 1); PG8_STAGE(PG8_SA(0, 0), a2, voffA);
;             PG8_BAR; PG8_WAIT_L(0); PG8_MMA(1, 0, At, B0); PG8_BAR; PG8_SCHED;
;             PG8_STAGE(PG8_SB(0, 1), b2 + hstepB, voffB);
;             PG8_WAIT_V(6); PG8_BAR; PG8_MMA(1, 1, At, B1); PG8_BAR;
;             PG8_LDB(B0, 1, 0); PG8_SCHED; PG8_LDA(At, 1, 0); PG8_STAGE(PG8_SA(0, 1), a2 + hstepA, voffA);
;             PG8_WAIT_L(8); PG8_BAR; PG8_WAIT_L(0); PG8_MMA(0, 0, At, B0); PG8_BAR; PG8_SCHED;
;             PG8_LDB(B1, 1, 1); PG8_STAGE(PG8_SB(1, 0), b3, voffB);
;             PG8_BAR; PG8_WAIT_L(0); PG8_MMA(0, 1, At, B1); PG8_BAR;
;             PG8_LDA(At, 1, 1); PG8_STAGE(PG8_SA(1, 0), a3, voffA);
;             PG8_BAR; PG8_WAIT_L(0); PG8_MMA(1, 0, At, B0); PG8_BAR; PG8_SCHED;
;             PG8_STAGE(PG8_SB(1, 1), b3 + hstepB, voffB);
;             PG8_WAIT_V(6); PG8_BAR; PG8_MMA(1, 1, At, B1); PG8_BAR;
	ds_read_b128 v[144:147], v209 offset:49152
	ds_read_b128 v[162:165], v209 offset:51200
	ds_read_b128 v[170:173], v209 offset:53248
	ds_read_b128 v[178:181], v209 offset:55296
	ds_read_b128 v[148:151], v209 offset:50176
	ds_read_b128 v[166:169], v209 offset:52224
	ds_read_b128 v[174:177], v209 offset:54272
	ds_read_b128 v[182:185], v209 offset:56320
	global_load_lds_dwordx4 v[202:203], off
	s_mov_b32 m0, s39
	v_lshl_add_u64 v[202:203], s[22:23], 0, v[156:157]
	global_load_lds_dwordx4 v[202:203], off
	s_add_u32 s22, s24, s52
	s_addc_u32 s23, s25, 0
	s_add_i32 s24, s26, s31
	s_mov_b32 m0, s24
	v_lshl_add_u64 v[202:203], s[22:23], 0, v[152:153]
	global_load_lds_dwordx4 v[202:203], off
	s_add_i32 m0, s24, 0x2000
	v_lshl_add_u64 v[202:203], s[22:23], 0, v[156:157]
	global_load_lds_dwordx4 v[202:203], off
	s_waitcnt vmcnt(6)
	s_waitcnt lgkmcnt(0)
	s_barrier
	v_mfma_f32_16x16x32_bf16 v[60:63], v[128:131], v[144:147], v[60:63]
	s_setprio 1
	v_mfma_f32_16x16x32_bf16 v[56:59], v[136:139], v[144:147], v[56:59]
	v_mfma_f32_16x16x32_bf16 v[52:55], v[128:131], v[162:165], v[52:55]
	v_mfma_f32_16x16x32_bf16 v[48:51], v[136:139], v[162:165], v[48:51]
	v_mfma_f32_16x16x32_bf16 v[44:47], v[128:131], v[170:173], v[44:47]
	v_mfma_f32_16x16x32_bf16 v[40:43], v[136:139], v[170:173], v[40:43]
	v_mfma_f32_16x16x32_bf16 v[36:39], v[128:131], v[178:181], v[36:39]
	v_mfma_f32_16x16x32_bf16 v[32:35], v[136:139], v[178:181], v[32:35]
	v_mfma_f32_16x16x32_bf16 v[60:63], v[132:135], v[148:151], v[60:63]
	v_mfma_f32_16x16x32_bf16 v[56:59], v[140:143], v[148:151], v[56:59]
	v_mfma_f32_16x16x32_bf16 v[52:55], v[132:135], v[166:169], v[52:55]
	v_mfma_f32_16x16x32_bf16 v[48:51], v[140:143], v[166:169], v[48:51]
	v_mfma_f32_16x16x32_bf16 v[44:47], v[132:135], v[174:177], v[44:47]
	v_mfma_f32_16x16x32_bf16 v[40:43], v[140:143], v[174:177], v[40:43]
	v_mfma_f32_16x16x32_bf16 v[36:39], v[132:135], v[182:185], v[36:39]
	v_mfma_f32_16x16x32_bf16 v[32:35], v[140:143], v[182:185], v[32:35]
	v_mfma_f32_16x16x32_bf16 v[28:31], v[186:189], v[144:147], v[28:31]
	v_mfma_f32_16x16x32_bf16 v[24:27], v[194:197], v[144:147], v[24:27]
	s_add_u32 s4, s4, 0x8000
	s_addc_u32 s5, s5, 0
	s_add_u32 s50, s50, 0x8000
	s_addc_u32 s51, s51, 0
	v_mfma_f32_16x16x32_bf16 v[20:23], v[186:189], v[162:165], v[20:23]
	v_mfma_f32_16x16x32_bf16 v[16:19], v[194:197], v[162:165], v[16:19]
	v_mfma_f32_16x16x32_bf16 v[12:15], v[186:189], v[170:173], v[12:15]
	v_mfma_f32_16x16x32_bf16 v[8:11], v[194:197], v[170:173], v[8:11]
	v_mfma_f32_16x16x32_bf16 v[4:7], v[186:189], v[178:181], v[4:7]
	v_mfma_f32_16x16x32_bf16 v[0:3], v[194:197], v[178:181], v[0:3]
	v_mfma_f32_16x16x32_bf16 v[28:31], v[190:193], v[148:151], v[28:31]
	v_mfma_f32_16x16x32_bf16 v[24:27], v[198:201], v[148:151], v[24:27]
	v_mfma_f32_16x16x32_bf16 v[20:23], v[190:193], v[166:169], v[20:23]
	v_mfma_f32_16x16x32_bf16 v[16:19], v[198:201], v[166:169], v[16:19]
	v_mfma_f32_16x16x32_bf16 v[12:15], v[190:193], v[174:177], v[12:15]
	v_mfma_f32_16x16x32_bf16 v[8:11], v[198:201], v[174:177], v[8:11]
	v_mfma_f32_16x16x32_bf16 v[4:7], v[190:193], v[182:185], v[4:7]
	s_cmp_ge_u32 s54, s28
	s_mov_b32 s22, s54
	s_setprio 0
	v_mfma_f32_16x16x32_bf16 v[0:3], v[198:201], v[182:185], v[0:3]
	s_barrier
	s_cbranch_scc0 .LBB0_187
	s_branch .Lpeel_done_187
.LBB0_187:
	s_add_i32 s54, s22, 2
	s_add_u32 s23, s4, 0x4000
	s_addc_u32 s24, s5, 0
	s_cmp_eq_u32 s40, s22
	s_cselect_b32 s26, s6, s23
	s_cselect_b32 s27, s7, s24
	s_cselect_b32 s24, s20, s50
	s_cselect_b32 s25, s21, s51
	s_add_u32 s22, s26, 0x4000
	s_addc_u32 s23, s27, 0
	s_add_i32 s55, 0, 0x10000
	v_add_u32_e32 v140, s55, v207
	ds_read_b128 v[128:131], v140
	ds_read_b128 v[136:139], v140 offset:2048
	ds_read_b128 v[132:135], v140 offset:1024
	ds_read_b128 v[140:143], v140 offset:3072
	v_lshl_add_u64 v[186:187], s[4:5], 0, v[158:159]
	s_add_i32 m0, s33, 0xc000
	ds_read_b128 v[144:147], v209
	ds_read_b128 v[162:165], v209 offset:2048
	ds_read_b128 v[170:173], v209 offset:4096
	ds_read_b128 v[178:181], v209 offset:6144
	ds_read_b128 v[148:151], v209 offset:1024
	ds_read_b128 v[166:169], v209 offset:3072
	ds_read_b128 v[174:177], v209 offset:5120
	ds_read_b128 v[182:185], v209 offset:7168
	global_load_lds_dwordx4 v[186:187], off
	s_add_i32 m0, s33, 0xe000
	v_lshl_add_u64 v[186:187], s[4:5], 0, v[160:161]
	global_load_lds_dwordx4 v[186:187], off
	s_waitcnt lgkmcnt(8)
	s_barrier
	s_waitcnt lgkmcnt(7)
	v_mfma_f32_16x16x32_bf16 v[124:127], v[128:131], v[144:147], v[124:127]
	s_setprio 1
	v_mfma_f32_16x16x32_bf16 v[120:123], v[136:139], v[144:147], v[120:123]
	s_waitcnt lgkmcnt(6)
	v_mfma_f32_16x16x32_bf16 v[116:119], v[128:131], v[162:165], v[116:119]
	v_mfma_f32_16x16x32_bf16 v[112:115], v[136:139], v[162:165], v[112:115]
	s_waitcnt lgkmcnt(5)
	v_mfma_f32_16x16x32_bf16 v[108:111], v[128:131], v[170:173], v[108:111]
	v_mfma_f32_16x16x32_bf16 v[104:107], v[136:139], v[170:173], v[104:107]
	s_waitcnt lgkmcnt(4)
	v_mfma_f32_16x16x32_bf16 v[100:103], v[128:131], v[178:181], v[100:103]
	v_mfma_f32_16x16x32_bf16 v[96:99], v[136:139], v[178:181], v[96:99]
	s_waitcnt lgkmcnt(3)
	v_mfma_f32_16x16x32_bf16 v[124:127], v[132:135], v[148:151], v[124:127]
	v_mfma_f32_16x16x32_bf16 v[120:123], v[140:143], v[148:151], v[120:123]
	s_waitcnt lgkmcnt(2)
	v_mfma_f32_16x16x32_bf16 v[116:119], v[132:135], v[166:169], v[116:119]
	v_mfma_f32_16x16x32_bf16 v[112:115], v[140:143], v[166:169], v[112:115]
	s_waitcnt lgkmcnt(1)
	v_mfma_f32_16x16x32_bf16 v[108:111], v[132:135], v[174:177], v[108:111]
	v_mfma_f32_16x16x32_bf16 v[104:107], v[140:143], v[174:177], v[104:107]
	s_waitcnt lgkmcnt(0)
	v_mfma_f32_16x16x32_bf16 v[100:103], v[132:135], v[182:185], v[100:103]
	s_setprio 0
	v_mfma_f32_16x16x32_bf16 v[96:99], v[140:143], v[182:185], v[96:99]
	s_barrier
; #define PG8_STAGE(bufoff, gbase, voff) do { _Pragma("unroll") for (int _i = 0; _i < 2; ++_i) \
;         __builtin_amdgcn_global_load_lds((const unsigned*)((const char*)(gbase) + (voff)[_i]), (LAS unsigned*)(lds + (bufoff) + ldsw + _i * 8192), 16, 0, 0); } while (0)
; #define PG8_LDA(dst, b, h) do { _Pragma("unroll") for (int m = 0; m < 4; ++m) _Pragma("unroll") for (int k = 0; k < 2; ++k) dst[m][k] = *(const LAS bf16x8*)(lds + PG8_SA(b, h) + aoff + m * 2048 + k * 1024); } while (0)
; #define PG8_LDB(dst, b, h) do { _Pragma("unroll") for (int n = 0; n < 2; ++n) _Pragma("unroll") for (int k = 0; k < 2; ++k) dst[n][k] = *(const LAS bf16x8*)(lds + PG8_SB(b, h) + boff + n * 2048 + k * 1024); } while (0)
; #define PG8_MMA(ai, bj, At, Bt) do { __builtin_amdgcn_s_setprio(1); _Pragma("unroll") for (int m = 0; m < 4; ++m) _Pragma("unroll") for (int n = 0; n < 2; ++n) _Pragma("unroll") for (int k = 0; k < 2; ++k) \
;         acc[ai][bj][m][n] = __builtin_amdgcn_mfma_f32_16x16x32_bf16(Bt[n][k], At[m][k], acc[ai][bj][m][n], 0, 0, 0); __builtin_amdgcn_s_setprio(0); } while (0)
; #define PG8_WAIT_V(n) asm volatile("s_waitcnt vmcnt(" #n ")" ::: "memory")
; #define PG8_WAIT_L(n) asm volatile("s_waitcnt lgkmcnt(" #n ")" ::: "memory")
; #define PG8_BAR __builtin_amdgcn_s_barrier()
; #define PG8_SCHED __builtin_amdgcn_sched_barrier(0)
; template <class Epi>
; __device__ __forceinline__ void gemm_phase(LAS unsigned char* lds, const Gemm g, const StaticOrder& S, const Epi& E) {
;     ...
;             PG8_LDB(B1, 0, 1); PG8_STAGE(PG8_SB(0, 0), b2, voffB);
;             PG8_BAR; PG8_WAIT_L(0); PG8_MMA(0, 1, At, B1); PG8_BAR;
;             PG8_LDA(At, 0, 1); PG8_STAGE(PG8_SA(0, 0), a2, voffA);
;             PG8_BAR; PG8_WAIT_L(0); PG8_MMA(1, 0, At, B0); PG8_BAR; PG8_SCHED;
;             PG8_STAGE(PG8_SB(0, 1), b2 + hstepB, voffB);
;             PG8_WAIT_V(6); PG8_BAR; PG8_MMA(1, 1, At, B1); PG8_BAR;
;             PG8_LDB(B0, 1, 0); PG8_SCHED; PG8_LDA(At, 1, 0); PG8_STAGE(PG8_SA(0, 1), a2 + hstepA, voffA);
;             PG8_WAIT_L(8); PG8_BAR; PG8_WAIT_L(0); PG8_MMA(0, 0, At, B0); PG8_BAR; PG8_SCHED;
	s_add_i32 s58, 0, 0x14000
	s_add_i32 s55, s55, s31
	v_add_u32_e32 v198, s58, v207
	v_lshl_add_u64 v[202:203], s[24:25], 0, v[152:153]
	s_mov_b32 m0, s55
	ds_read_b128 v[186:189], v198
	ds_read_b128 v[194:197], v198 offset:2048
	ds_read_b128 v[190:193], v198 offset:1024
	ds_read_b128 v[198:201], v198 offset:3072
	global_load_lds_dwordx4 v[202:203], off
	s_add_i32 m0, s55, 0x2000
	v_lshl_add_u64 v[202:203], s[24:25], 0, v[156:157]
	global_load_lds_dwordx4 v[202:203], off
	s_waitcnt lgkmcnt(0)
	s_barrier
	v_mfma_f32_16x16x32_bf16 v[92:95], v[186:189], v[144:147], v[92:95]
	s_setprio 1
	v_mfma_f32_16x16x32_bf16 v[88:91], v[194:197], v[144:147], v[88:91]
	s_mov_b32 m0, s33
	v_lshl_add_u64 v[202:203], s[26:27], 0, v[152:153]
	v_mfma_f32_16x16x32_bf16 v[84:87], v[186:189], v[162:165], v[84:87]
	v_mfma_f32_16x16x32_bf16 v[80:83], v[194:197], v[162:165], v[80:83]
	v_mfma_f32_16x16x32_bf16 v[76:79], v[186:189], v[170:173], v[76:79]
	v_mfma_f32_16x16x32_bf16 v[72:75], v[194:197], v[170:173], v[72:75]
	v_mfma_f32_16x16x32_bf16 v[68:71], v[186:189], v[178:181], v[68:71]
	v_mfma_f32_16x16x32_bf16 v[64:67], v[194:197], v[178:181], v[64:67]
	v_mfma_f32_16x16x32_bf16 v[92:95], v[190:193], v[148:151], v[92:95]
	v_mfma_f32_16x16x32_bf16 v[88:91], v[198:201], v[148:151], v[88:91]
	v_mfma_f32_16x16x32_bf16 v[84:87], v[190:193], v[166:169], v[84:87]
	v_mfma_f32_16x16x32_bf16 v[80:83], v[198:201], v[166:169], v[80:83]
	v_mfma_f32_16x16x32_bf16 v[76:79], v[190:193], v[174:177], v[76:79]
	v_mfma_f32_16x16x32_bf16 v[72:75], v[198:201], v[174:177], v[72:75]
	v_mfma_f32_16x16x32_bf16 v[68:71], v[190:193], v[182:185], v[68:71]
	s_setprio 0
	v_mfma_f32_16x16x32_bf16 v[64:67], v[198:201], v[182:185], v[64:67]
	s_barrier
	ds_read_b128 v[144:147], v209 offset:16384
	ds_read_b128 v[162:165], v209 offset:18432
	ds_read_b128 v[170:173], v209 offset:20480
	ds_read_b128 v[178:181], v209 offset:22528
	ds_read_b128 v[148:151], v209 offset:17408
	ds_read_b128 v[166:169], v209 offset:19456
	ds_read_b128 v[174:177], v209 offset:21504
	ds_read_b128 v[182:185], v209 offset:23552
	global_load_lds_dwordx4 v[202:203], off
	s_mov_b32 m0, s34
	v_lshl_add_u64 v[202:203], s[26:27], 0, v[156:157]
	global_load_lds_dwordx4 v[202:203], off
	s_add_u32 s56, s24, s52
	s_addc_u32 s57, s25, 0
	s_add_i32 s55, s58, s31
	s_mov_b32 m0, s55
	v_lshl_add_u64 v[202:203], s[56:57], 0, v[152:153]
	global_load_lds_dwordx4 v[202:203], off
	s_add_i32 m0, s55, 0x2000
	v_lshl_add_u64 v[202:203], s[56:57], 0, v[156:157]
	global_load_lds_dwordx4 v[202:203], off
	s_waitcnt vmcnt(6)
	s_waitcnt lgkmcnt(0)
	s_barrier
	v_mfma_f32_16x16x32_bf16 v[60:63], v[128:131], v[144:147], v[60:63]
	s_setprio 1
	v_mfma_f32_16x16x32_bf16 v[56:59], v[136:139], v[144:147], v[56:59]
	v_mfma_f32_16x16x32_bf16 v[52:55], v[128:131], v[162:165], v[52:55]
	v_mfma_f32_16x16x32_bf16 v[48:51], v[136:139], v[162:165], v[48:51]
	v_mfma_f32_16x16x32_bf16 v[44:47], v[128:131], v[170:173], v[44:47]
	v_mfma_f32_16x16x32_bf16 v[40:43], v[136:139], v[170:173], v[40:43]
	v_mfma_f32_16x16x32_bf16 v[36:39], v[128:131], v[178:181], v[36:39]
	v_mfma_f32_16x16x32_bf16 v[32:35], v[136:139], v[178:181], v[32:35]
	v_mfma_f32_16x16x32_bf16 v[60:63], v[132:135], v[148:151], v[60:63]
	v_mfma_f32_16x16x32_bf16 v[56:59], v[140:143], v[148:151], v[56:59]
	v_mfma_f32_16x16x32_bf16 v[52:55], v[132:135], v[166:169], v[52:55]
	v_mfma_f32_16x16x32_bf16 v[48:51], v[140:143], v[166:169], v[48:51]
	v_mfma_f32_16x16x32_bf16 v[44:47], v[132:135], v[174:177], v[44:47]
	v_mfma_f32_16x16x32_bf16 v[40:43], v[140:143], v[174:177], v[40:43]
	v_mfma_f32_16x16x32_bf16 v[36:39], v[132:135], v[182:185], v[36:39]
	v_mfma_f32_16x16x32_bf16 v[32:35], v[140:143], v[182:185], v[32:35]
	v_mfma_f32_16x16x32_bf16 v[28:31], v[186:189], v[144:147], v[28:31]
	v_mfma_f32_16x16x32_bf16 v[24:27], v[194:197], v[144:147], v[24:27]
	s_add_i32 s55, 0, 0x18000
	v_add_u32_e32 v140, s55, v207
	v_mfma_f32_16x16x32_bf16 v[20:23], v[186:189], v[162:165], v[20:23]
	v_mfma_f32_16x16x32_bf16 v[16:19], v[194:197], v[162:165], v[16:19]
	v_mfma_f32_16x16x32_bf16 v[12:15], v[186:189], v[170:173], v[12:15]
	v_mfma_f32_16x16x32_bf16 v[8:11], v[194:197], v[170:173], v[8:11]
	v_mfma_f32_16x16x32_bf16 v[4:7], v[186:189], v[178:181], v[4:7]
	v_mfma_f32_16x16x32_bf16 v[0:3], v[194:197], v[178:181], v[0:3]
	v_mfma_f32_16x16x32_bf16 v[28:31], v[190:193], v[148:151], v[28:31]
	v_mfma_f32_16x16x32_bf16 v[24:27], v[198:201], v[148:151], v[24:27]
	v_mfma_f32_16x16x32_bf16 v[20:23], v[190:193], v[166:169], v[20:23]
	v_mfma_f32_16x16x32_bf16 v[16:19], v[198:201], v[166:169], v[16:19]
	v_mfma_f32_16x16x32_bf16 v[12:15], v[190:193], v[174:177], v[12:15]
	v_mfma_f32_16x16x32_bf16 v[8:11], v[198:201], v[174:177], v[8:11]
	v_mfma_f32_16x16x32_bf16 v[4:7], v[190:193], v[182:185], v[4:7]
	s_setprio 0
	v_mfma_f32_16x16x32_bf16 v[0:3], v[198:201], v[182:185], v[0:3]
	s_barrier
	ds_read_b128 v[128:131], v140
	ds_read_b128 v[136:139], v140 offset:2048
	ds_read_b128 v[132:135], v140 offset:1024
	ds_read_b128 v[140:143], v140 offset:3072
	s_add_u32 s26, s26, s52
	s_addc_u32 s27, s27, 0
	s_mov_b32 m0, s35
	v_lshl_add_u64 v[186:187], s[26:27], 0, v[152:153]
	ds_read_b128 v[144:147], v209 offset:32768
	ds_read_b128 v[162:165], v209 offset:34816
	ds_read_b128 v[170:173], v209 offset:36864
	ds_read_b128 v[178:181], v209 offset:38912
	ds_read_b128 v[148:151], v209 offset:33792
	ds_read_b128 v[166:169], v209 offset:35840
	ds_read_b128 v[174:177], v209 offset:37888
	ds_read_b128 v[182:185], v209 offset:39936
	global_load_lds_dwordx4 v[186:187], off
	s_mov_b32 m0, s36
	v_lshl_add_u64 v[186:187], s[26:27], 0, v[156:157]
	global_load_lds_dwordx4 v[186:187], off
	s_waitcnt lgkmcnt(8)
	s_barrier
; #define PG8_STAGE(bufoff, gbase, voff) do { _Pragma("unroll") for (int _i = 0; _i < 2; ++_i) \
;         __builtin_amdgcn_global_load_lds((const unsigned*)((const char*)(gbase) + (voff)[_i]), (LAS unsigned*)(lds + (bufoff) + ldsw + _i * 8192), 16, 0, 0); } while (0)
; #define PG8_LDA(dst, b, h) do { _Pragma("unroll") for (int m = 0; m < 4; ++m) _Pragma("unroll") for (int k = 0; k < 2; ++k) dst[m][k] = *(const LAS bf16x8*)(lds + PG8_SA(b, h) + aoff + m * 2048 + k * 1024); } while (0)
; #define PG8_LDB(dst, b, h) do { _Pragma("unroll") for (int n = 0; n < 2; ++n) _Pragma("unroll") for (int k = 0; k < 2; ++k) dst[n][k] = *(const LAS bf16x8*)(lds + PG8_SB(b, h) + boff + n * 2048 + k * 1024); } while (0)
; #define PG8_MMA(ai, bj, At, Bt) do { __builtin_amdgcn_s_setprio(1); _Pragma("unroll") for (int m = 0; m < 4; ++m) _Pragma("unroll") for (int n = 0; n < 2; ++n) _Pragma("unroll") for (int k = 0; k < 2; ++k) \
;         acc[ai][bj][m][n] = __builtin_amdgcn_mfma_f32_16x16x32_bf16(Bt[n][k], At[m][k], acc[ai][bj][m][n], 0, 0, 0); __builtin_amdgcn_s_setprio(0); } while (0)
; #define PG8_WAIT_V(n) asm volatile("s_waitcnt vmcnt(" #n ")" ::: "memory")
; #define PG8_WAIT_L(n) asm volatile("s_waitcnt lgkmcnt(" #n ")" ::: "memory")
; #define PG8_BAR __builtin_amdgcn_s_barrier()
; #define PG8_SCHED __builtin_amdgcn_sched_barrier(0)
; template <class Epi>
; __device__ __forceinline__ void gemm_phase(LAS unsigned char* lds, const Gemm g, const StaticOrder& S, const Epi& E) {
;     ...
;             PG8_WAIT_L(8); PG8_BAR; PG8_WAIT_L(0); PG8_MMA(0, 0, At, B0); PG8_BAR; PG8_SCHED;
;             PG8_LDB(B1, 1, 1); PG8_STAGE(PG8_SB(1, 0), b3, voffB);
;             PG8_BAR; PG8_WAIT_L(0); PG8_MMA(0, 1, At, B1); PG8_BAR;
;             PG8_LDA(At, 1, 1); PG8_STAGE(PG8_SA(1, 0), a3, voffA);
;             PG8_BAR; PG8_WAIT_L(0); PG8_MMA(1, 0, At, B0); PG8_BAR; PG8_SCHED;
;             PG8_STAGE(PG8_SB(1, 1), b3 + hstepB, voffB);
;             PG8_WAIT_V(6); PG8_BAR; PG8_MMA(1, 1, At, B1); PG8_BAR;
	s_waitcnt lgkmcnt(7)
	v_mfma_f32_16x16x32_bf16 v[124:127], v[128:131], v[144:147], v[124:127]
	s_setprio 1
	v_mfma_f32_16x16x32_bf16 v[120:123], v[136:139], v[144:147], v[120:123]
	s_waitcnt lgkmcnt(6)
	v_mfma_f32_16x16x32_bf16 v[116:119], v[128:131], v[162:165], v[116:119]
	v_mfma_f32_16x16x32_bf16 v[112:115], v[136:139], v[162:165], v[112:115]
	s_waitcnt lgkmcnt(5)
	v_mfma_f32_16x16x32_bf16 v[108:111], v[128:131], v[170:173], v[108:111]
	v_mfma_f32_16x16x32_bf16 v[104:107], v[136:139], v[170:173], v[104:107]
	s_waitcnt lgkmcnt(4)
	v_mfma_f32_16x16x32_bf16 v[100:103], v[128:131], v[178:181], v[100:103]
	v_mfma_f32_16x16x32_bf16 v[96:99], v[136:139], v[178:181], v[96:99]
	s_waitcnt lgkmcnt(3)
	v_mfma_f32_16x16x32_bf16 v[124:127], v[132:135], v[148:151], v[124:127]
	v_mfma_f32_16x16x32_bf16 v[120:123], v[140:143], v[148:151], v[120:123]
	s_waitcnt lgkmcnt(2)
	v_mfma_f32_16x16x32_bf16 v[116:119], v[132:135], v[166:169], v[116:119]
	v_mfma_f32_16x16x32_bf16 v[112:115], v[140:143], v[166:169], v[112:115]
	s_waitcnt lgkmcnt(1)
	v_mfma_f32_16x16x32_bf16 v[108:111], v[132:135], v[174:177], v[108:111]
	v_mfma_f32_16x16x32_bf16 v[104:107], v[140:143], v[174:177], v[104:107]
	s_waitcnt lgkmcnt(0)
	v_mfma_f32_16x16x32_bf16 v[100:103], v[132:135], v[182:185], v[100:103]
	s_setprio 0
	v_mfma_f32_16x16x32_bf16 v[96:99], v[140:143], v[182:185], v[96:99]
	s_barrier
	s_add_i32 s26, 0, 0x1c000
	s_add_u32 s24, s24, 0x4000
	s_addc_u32 s25, s25, 0
	s_add_i32 s27, s55, s31
	v_add_u32_e32 v198, s26, v207
	v_lshl_add_u64 v[202:203], s[24:25], 0, v[152:153]
	s_mov_b32 m0, s27
	ds_read_b128 v[186:189], v198
	ds_read_b128 v[194:197], v198 offset:2048
	ds_read_b128 v[190:193], v198 offset:1024
	ds_read_b128 v[198:201], v198 offset:3072
	global_load_lds_dwordx4 v[202:203], off
	s_add_i32 m0, s27, 0x2000
	v_lshl_add_u64 v[202:203], s[24:25], 0, v[156:157]
	global_load_lds_dwordx4 v[202:203], off
	s_waitcnt lgkmcnt(0)
	s_barrier
	v_mfma_f32_16x16x32_bf16 v[92:95], v[186:189], v[144:147], v[92:95]
	s_setprio 1
	v_mfma_f32_16x16x32_bf16 v[88:91], v[194:197], v[144:147], v[88:91]
	s_mov_b32 m0, s38
	v_lshl_add_u64 v[202:203], s[22:23], 0, v[152:153]
	v_mfma_f32_16x16x32_bf16 v[84:87], v[186:189], v[162:165], v[84:87]
	v_mfma_f32_16x16x32_bf16 v[80:83], v[194:197], v[162:165], v[80:83]
	v_mfma_f32_16x16x32_bf16 v[76:79], v[186:189], v[170:173], v[76:79]
	v_mfma_f32_16x16x32_bf16 v[72:75], v[194:197], v[170:173], v[72:75]
	v_mfma_f32_16x16x32_bf16 v[68:71], v[186:189], v[178:181], v[68:71]
	v_mfma_f32_16x16x32_bf16 v[64:67], v[194:197], v[178:181], v[64:67]
	v_mfma_f32_16x16x32_bf16 v[92:95], v[190:193], v[148:151], v[92:95]
	v_mfma_f32_16x16x32_bf16 v[88:91], v[198:201], v[148:151], v[88:91]
	v_mfma_f32_16x16x32_bf16 v[84:87], v[190:193], v[166:169], v[84:87]
	v_mfma_f32_16x16x32_bf16 v[80:83], v[198:201], v[166:169], v[80:83]
	v_mfma_f32_16x16x32_bf16 v[76:79], v[190:193], v[174:177], v[76:79]
	v_mfma_f32_16x16x32_bf16 v[72:75], v[198:201], v[174:177], v[72:75]
	v_mfma_f32_16x16x32_bf16 v[68:71], v[190:193], v[182:185], v[68:71]
	s_setprio 0
	v_mfma_f32_16x16x32_bf16 v[64:67], v[198:201], v[182:185], v[64:67]
	s_barrier
	ds_read_b128 v[144:147], v209 offset:49152
	ds_read_b128 v[162:165], v209 offset:51200
	ds_read_b128 v[170:173], v209 offset:53248
	ds_read_b128 v[178:181], v209 offset:55296
	ds_read_b128 v[148:151], v209 offset:50176
	ds_read_b128 v[166:169], v209 offset:52224
	ds_read_b128 v[174:177], v209 offset:54272
	ds_read_b128 v[182:185], v209 offset:56320
	global_load_lds_dwordx4 v[202:203], off
	s_mov_b32 m0, s39
	v_lshl_add_u64 v[202:203], s[22:23], 0, v[156:157]
	global_load_lds_dwordx4 v[202:203], off
	s_add_u32 s22, s24, s52
	s_addc_u32 s23, s25, 0
	s_add_i32 s24, s26, s31
	s_mov_b32 m0, s24
	v_lshl_add_u64 v[202:203], s[22:23], 0, v[152:153]
	global_load_lds_dwordx4 v[202:203], off
	s_add_i32 m0, s24, 0x2000
	v_lshl_add_u64 v[202:203], s[22:23], 0, v[156:157]
	global_load_lds_dwordx4 v[202:203], off
	s_waitcnt vmcnt(6)
	s_waitcnt lgkmcnt(0)
	s_barrier
	v_mfma_f32_16x16x32_bf16 v[60:63], v[128:131], v[144:147], v[60:63]
	s_setprio 1
	v_mfma_f32_16x16x32_bf16 v[56:59], v[136:139], v[144:147], v[56:59]
	v_mfma_f32_16x16x32_bf16 v[52:55], v[128:131], v[162:165], v[52:55]
	v_mfma_f32_16x16x32_bf16 v[48:51], v[136:139], v[162:165], v[48:51]
	v_mfma_f32_16x16x32_bf16 v[44:47], v[128:131], v[170:173], v[44:47]
	v_mfma_f32_16x16x32_bf16 v[40:43], v[136:139], v[170:173], v[40:43]
	v_mfma_f32_16x16x32_bf16 v[36:39], v[128:131], v[178:181], v[36:39]
	v_mfma_f32_16x16x32_bf16 v[32:35], v[136:139], v[178:181], v[32:35]
	v_mfma_f32_16x16x32_bf16 v[60:63], v[132:135], v[148:151], v[60:63]
	v_mfma_f32_16x16x32_bf16 v[56:59], v[140:143], v[148:151], v[56:59]
	v_mfma_f32_16x16x32_bf16 v[52:55], v[132:135], v[166:169], v[52:55]
	v_mfma_f32_16x16x32_bf16 v[48:51], v[140:143], v[166:169], v[48:51]
	v_mfma_f32_16x16x32_bf16 v[44:47], v[132:135], v[174:177], v[44:47]
	v_mfma_f32_16x16x32_bf16 v[40:43], v[140:143], v[174:177], v[40:43]
	v_mfma_f32_16x16x32_bf16 v[36:39], v[132:135], v[182:185], v[36:39]
	v_mfma_f32_16x16x32_bf16 v[32:35], v[140:143], v[182:185], v[32:35]
	v_mfma_f32_16x16x32_bf16 v[28:31], v[186:189], v[144:147], v[28:31]
	v_mfma_f32_16x16x32_bf16 v[24:27], v[194:197], v[144:147], v[24:27]
	s_add_u32 s4, s4, 0x8000
	s_addc_u32 s5, s5, 0
	s_add_u32 s50, s50, 0x8000
	s_addc_u32 s51, s51, 0
	v_mfma_f32_16x16x32_bf16 v[20:23], v[186:189], v[162:165], v[20:23]
	v_mfma_f32_16x16x32_bf16 v[16:19], v[194:197], v[162:165], v[16:19]
	v_mfma_f32_16x16x32_bf16 v[12:15], v[186:189], v[170:173], v[12:15]
	v_mfma_f32_16x16x32_bf16 v[8:11], v[194:197], v[170:173], v[8:11]
	v_mfma_f32_16x16x32_bf16 v[4:7], v[186:189], v[178:181], v[4:7]
	v_mfma_f32_16x16x32_bf16 v[0:3], v[194:197], v[178:181], v[0:3]
	v_mfma_f32_16x16x32_bf16 v[28:31], v[190:193], v[148:151], v[28:31]
	v_mfma_f32_16x16x32_bf16 v[24:27], v[198:201], v[148:151], v[24:27]
	v_mfma_f32_16x16x32_bf16 v[20:23], v[190:193], v[166:169], v[20:23]
	v_mfma_f32_16x16x32_bf16 v[16:19], v[198:201], v[166:169], v[16:19]
	v_mfma_f32_16x16x32_bf16 v[12:15], v[190:193], v[174:177], v[12:15]
	v_mfma_f32_16x16x32_bf16 v[8:11], v[198:201], v[174:177], v[8:11]
	v_mfma_f32_16x16x32_bf16 v[4:7], v[190:193], v[182:185], v[4:7]
	s_cmp_ge_u32 s54, s28
	s_mov_b32 s22, s54
	s_setprio 0
	v_mfma_f32_16x16x32_bf16 v[0:3], v[198:201], v[182:185], v[0:3]
	s_barrier
	s_cbranch_scc0 .LBB0_187

; #define PG8_STAGE(bufoff, gbase, voff) do { _Pragma("unroll") for (int _i = 0; _i < 2; ++_i) \
;         __builtin_amdgcn_global_load_lds((const unsigned*)((const char*)(gbase) + (voff)[_i]), (LAS unsigned*)(lds + (bufoff) + ldsw + _i * 8192), 16, 0, 0); } while (0)
; #define PG8_LDA(dst, b, h) do { _Pragma("unroll") for (int m = 0; m < 4; ++m) _Pragma("unroll") for (int k = 0; k < 2; ++k) dst[m][k] = *(const LAS bf16x8*)(lds + PG8_SA(b, h) + aoff + m * 2048 + k * 1024); } while (0)
; #define PG8_LDB(dst, b, h) do { _Pragma("unroll") for (int n = 0; n < 2; ++n) _Pragma("unroll") for (int k = 0; k < 2; ++k) dst[n][k] = *(const LAS bf16x8*)(lds + PG8_SB(b, h) + boff + n * 2048 + k * 1024); } while (0)
; #define PG8_WAIT_V(n) asm volatile("s_waitcnt vmcnt(" #n ")" ::: "memory")
; #define PG8_WAIT_L(n) asm volatile("s_waitcnt lgkmcnt(" #n ")" ::: "memory")
; #define PG8_BAR __builtin_amdgcn_s_barrier()
; #define PG8_SCHED __builtin_amdgcn_sched_barrier(0)
; template <class Epi>
; __device__ __forceinline__ void gemm_phase(LAS unsigned char* lds, const Gemm g, const StaticOrder& S, const Epi& E) {
;     ...
;         const bool has_next = S.next(ui + 1, nxt);
;         const char* nA = has_next ? (const char*)g.A + (size_t)nxt.pm * tstepA : cA; const char* nB = has_next ? (const char*)g.Bt + (size_t)nxt.pn * tstepB : cB;
;         for (int t = 0; t < nt; t += 2) {
;             const bool last = (t == nt - 2);
;             const char* a1 = cA + (size_t)(t + 1) * kstep;
;             const char* a2 = last ? nA : cA + (size_t)(t + 2) * kstep; const char* b2 = last ? nB : cB + (size_t)(t + 2) * kstep;
;             const char* a3 = a2 + kstep; const char* b3 = b2 + kstep;
;             PG8_LDB(B0, 0, 0); PG8_SCHED; PG8_LDA(At, 0, 0); PG8_STAGE(PG8_SA(1, 1), a1 + hstepA, voffA);
;             PG8_WAIT_L(8); PG8_BAR; PG8_WAIT_L(0); PG8_MMA(0, 0, At, B0); PG8_BAR; PG8_SCHED;
;             PG8_LDB(B1, 0, 1); PG8_STAGE(PG8_SB(0, 0), b2, voffB);
;             PG8_BAR; PG8_WAIT_L(0); PG8_MMA(0, 1, At, B1); PG8_BAR;
;             PG8_LDA(At, 0, 1); PG8_STAGE(PG8_SA(0, 0), a2, voffA);
;             PG8_BAR; PG8_WAIT_L(0); PG8_MMA(1, 0, At, B0); PG8_BAR; PG8_SCHED;
;             PG8_STAGE(PG8_SB(0, 1), b2 + hstepB, voffB);
;             PG8_WAIT_V(6); PG8_BAR; PG8_MMA(1, 1, At, B1); PG8_BAR;
.LBB0_246:
	s_ashr_i32 s5, s4, 31
	v_cmp_lt_i64_e32 vcc, s[6:7], v[154:155]
	s_lshl_b64 s[6:7], s[4:5], 20
	v_readlane_b32 s8, v252, 53
	v_readlane_b32 s9, v252, 54
	s_add_u32 s6, s8, s6
	s_addc_u32 s7, s9, s7
	s_and_b64 s[8:9], vcc, exec
	s_cselect_b32 s5, s7, s13
	s_cselect_b32 s11, s6, s12
	s_ashr_i32 s3, s2, 31
	s_lshl_b64 s[8:9], s[2:3], 20
	s_add_u32 s8, s21, s8
	s_addc_u32 s9, s22, s9
	s_and_b64 s[16:17], vcc, exec
	s_cselect_b32 s3, s9, s15
	s_cselect_b32 s35, s8, s14
	s_add_u32 s12, s12, 0x84000
	s_addc_u32 s13, s13, 0
	s_add_u32 s36, s14, 0x8000
	s_addc_u32 s37, s15, 0
	s_mov_b32 s38, -2
	s_add_u32 s14, s12, 0xfff84000
	s_addc_u32 s15, s13, -1
	s_cmp_eq_u32 s38, 28
	s_cselect_b32 s18, s11, s14
	s_cselect_b32 s19, s5, s15
	s_cselect_b32 s14, s35, s36
	s_cselect_b32 s15, s3, s37
	s_add_u32 s16, s18, 0x4000
	s_addc_u32 s17, s19, 0
	s_add_i32 s39, 0, 0x10000
	v_add_u32_e32 v140, s39, v170
	ds_read_b128 v[128:131], v140
	ds_read_b128 v[136:139], v140 offset:2048
	ds_read_b128 v[132:135], v140 offset:1024
	ds_read_b128 v[140:143], v140 offset:3072
	v_lshl_add_u64 v[194:195], s[12:13], 0, v[156:157]
	s_add_i32 m0, s25, 0xc000
	ds_read_b128 v[144:147], v172
	ds_read_b128 v[166:169], v172 offset:2048
	ds_read_b128 v[178:181], v172 offset:4096
	ds_read_b128 v[186:189], v172 offset:6144
	ds_read_b128 v[148:151], v172 offset:1024
	ds_read_b128 v[174:177], v172 offset:3072
	ds_read_b128 v[182:185], v172 offset:5120
	ds_read_b128 v[190:193], v172 offset:7168
	global_load_lds_dwordx4 v[194:195], off
	s_add_i32 m0, s25, 0xe000
	v_lshl_add_u64 v[194:195], s[12:13], 0, v[158:159]
	global_load_lds_dwordx4 v[194:195], off
	s_waitcnt lgkmcnt(8)
	s_barrier
	s_waitcnt lgkmcnt(7)
	v_mfma_f32_16x16x32_bf16 v[124:127], v[128:131], v[144:147], 0
	s_setprio 1
	v_mfma_f32_16x16x32_bf16 v[120:123], v[136:139], v[144:147], 0
	s_waitcnt lgkmcnt(6)
	v_mfma_f32_16x16x32_bf16 v[108:111], v[128:131], v[166:169], 0
	v_mfma_f32_16x16x32_bf16 v[104:107], v[136:139], v[166:169], 0
	s_waitcnt lgkmcnt(5)
	v_mfma_f32_16x16x32_bf16 v[92:95], v[128:131], v[178:181], 0
	v_mfma_f32_16x16x32_bf16 v[88:91], v[136:139], v[178:181], 0
	s_waitcnt lgkmcnt(4)
	v_mfma_f32_16x16x32_bf16 v[76:79], v[128:131], v[186:189], 0
	v_mfma_f32_16x16x32_bf16 v[72:75], v[136:139], v[186:189], 0
	s_waitcnt lgkmcnt(3)
	v_mfma_f32_16x16x32_bf16 v[124:127], v[132:135], v[148:151], v[124:127]
	v_mfma_f32_16x16x32_bf16 v[120:123], v[140:143], v[148:151], v[120:123]
	s_waitcnt lgkmcnt(2)
	v_mfma_f32_16x16x32_bf16 v[108:111], v[132:135], v[174:177], v[108:111]
	v_mfma_f32_16x16x32_bf16 v[104:107], v[140:143], v[174:177], v[104:107]
	s_waitcnt lgkmcnt(1)
	v_mfma_f32_16x16x32_bf16 v[92:95], v[132:135], v[182:185], v[92:95]
	v_mfma_f32_16x16x32_bf16 v[88:91], v[140:143], v[182:185], v[88:91]
	s_waitcnt lgkmcnt(0)
	v_mfma_f32_16x16x32_bf16 v[76:79], v[132:135], v[190:193], v[76:79]
	s_setprio 0
	v_mfma_f32_16x16x32_bf16 v[72:75], v[140:143], v[190:193], v[72:75]
	s_barrier
	s_add_i32 s42, 0, 0x14000
	s_add_i32 s39, s39, s23
	v_add_u32_e32 v152, s42, v170
	v_lshl_add_u64 v[210:211], s[14:15], 0, v[156:157]
	s_mov_b32 m0, s39
	ds_read_b128 v[194:197], v152
	ds_read_b128 v[202:205], v152 offset:2048
	ds_read_b128 v[198:201], v152 offset:1024
	ds_read_b128 v[206:209], v152 offset:3072
	global_load_lds_dwordx4 v[210:211], off
	s_add_i32 m0, s39, 0x2000
	v_lshl_add_u64 v[210:211], s[14:15], 0, v[158:159]
	global_load_lds_dwordx4 v[210:211], off
	s_waitcnt lgkmcnt(0)
	s_barrier
	v_mfma_f32_16x16x32_bf16 v[116:119], v[194:197], v[144:147], 0
	s_setprio 1
	v_mfma_f32_16x16x32_bf16 v[112:115], v[202:205], v[144:147], 0
	s_mov_b32 m0, s25
	v_lshl_add_u64 v[210:211], s[18:19], 0, v[156:157]
	v_mfma_f32_16x16x32_bf16 v[100:103], v[194:197], v[166:169], 0
	v_mfma_f32_16x16x32_bf16 v[96:99], v[202:205], v[166:169], 0
	v_mfma_f32_16x16x32_bf16 v[84:87], v[194:197], v[178:181], 0
	v_mfma_f32_16x16x32_bf16 v[80:83], v[202:205], v[178:181], 0
	v_mfma_f32_16x16x32_bf16 v[68:71], v[194:197], v[186:189], 0
	v_mfma_f32_16x16x32_bf16 v[64:67], v[202:205], v[186:189], 0
	v_mfma_f32_16x16x32_bf16 v[116:119], v[198:201], v[148:151], v[116:119]
	v_mfma_f32_16x16x32_bf16 v[112:115], v[206:209], v[148:151], v[112:115]
	v_mfma_f32_16x16x32_bf16 v[100:103], v[198:201], v[174:177], v[100:103]
	v_mfma_f32_16x16x32_bf16 v[96:99], v[206:209], v[174:177], v[96:99]
	v_mfma_f32_16x16x32_bf16 v[84:87], v[198:201], v[182:185], v[84:87]
	v_mfma_f32_16x16x32_bf16 v[80:83], v[206:209], v[182:185], v[80:83]
	v_mfma_f32_16x16x32_bf16 v[68:71], v[198:201], v[190:193], v[68:71]
	s_setprio 0
	v_mfma_f32_16x16x32_bf16 v[64:67], v[206:209], v[190:193], v[64:67]
	s_barrier
	ds_read_b128 v[144:147], v172 offset:16384
	ds_read_b128 v[166:169], v172 offset:18432
	ds_read_b128 v[178:181], v172 offset:20480
	ds_read_b128 v[186:189], v172 offset:22528
	ds_read_b128 v[148:151], v172 offset:17408
	ds_read_b128 v[174:177], v172 offset:19456
	ds_read_b128 v[182:185], v172 offset:21504
	ds_read_b128 v[190:193], v172 offset:23552
	global_load_lds_dwordx4 v[210:211], off
	s_mov_b32 m0, s26
	v_lshl_add_u64 v[210:211], s[18:19], 0, v[158:159]
	global_load_lds_dwordx4 v[210:211], off
	s_add_u32 s40, s14, 0x80000
	s_addc_u32 s41, s15, 0
	s_add_i32 s39, s42, s23
	s_mov_b32 m0, s39
	v_lshl_add_u64 v[210:211], s[40:41], 0, v[156:157]
	global_load_lds_dwordx4 v[210:211], off
	s_add_i32 m0, s39, 0x2000
	v_lshl_add_u64 v[210:211], s[40:41], 0, v[158:159]
	global_load_lds_dwordx4 v[210:211], off
	s_waitcnt vmcnt(6)
	s_waitcnt lgkmcnt(0)
	s_barrier
; #define PG8_STAGE(bufoff, gbase, voff) do { _Pragma("unroll") for (int _i = 0; _i < 2; ++_i) \
;         __builtin_amdgcn_global_load_lds((const unsigned*)((const char*)(gbase) + (voff)[_i]), (LAS unsigned*)(lds + (bufoff) + ldsw + _i * 8192), 16, 0, 0); } while (0)
; #define PG8_LDA(dst, b, h) do { _Pragma("unroll") for (int m = 0; m < 4; ++m) _Pragma("unroll") for (int k = 0; k < 2; ++k) dst[m][k] = *(const LAS bf16x8*)(lds + PG8_SA(b, h) + aoff + m * 2048 + k * 1024); } while (0)
; #define PG8_LDB(dst, b, h) do { _Pragma("unroll") for (int n = 0; n < 2; ++n) _Pragma("unroll") for (int k = 0; k < 2; ++k) dst[n][k] = *(const LAS bf16x8*)(lds + PG8_SB(b, h) + boff + n * 2048 + k * 1024); } while (0)
; #define PG8_MMA(ai, bj, At, Bt) do { __builtin_amdgcn_s_setprio(1); _Pragma("unroll") for (int m = 0; m < 4; ++m) _Pragma("unroll") for (int n = 0; n < 2; ++n) _Pragma("unroll") for (int k = 0; k < 2; ++k) \
;         acc[ai][bj][m][n] = __builtin_amdgcn_mfma_f32_16x16x32_bf16(Bt[n][k], At[m][k], acc[ai][bj][m][n], 0, 0, 0); __builtin_amdgcn_s_setprio(0); } while (0)
; #define PG8_WAIT_V(n) asm volatile("s_waitcnt vmcnt(" #n ")" ::: "memory")
; #define PG8_WAIT_L(n) asm volatile("s_waitcnt lgkmcnt(" #n ")" ::: "memory")
; #define PG8_BAR __builtin_amdgcn_s_barrier()
; #define PG8_SCHED __builtin_amdgcn_sched_barrier(0)
; template <class Epi>
; __device__ __forceinline__ void gemm_phase(LAS unsigned char* lds, const Gemm g, const StaticOrder& S, const Epi& E) {
;     ...
;             PG8_BAR; PG8_WAIT_L(0); PG8_MMA(1, 0, At, B0); PG8_BAR; PG8_SCHED;
;             PG8_STAGE(PG8_SB(0, 1), b2 + hstepB, voffB);
;             PG8_WAIT_V(6); PG8_BAR; PG8_MMA(1, 1, At, B1); PG8_BAR;
;             PG8_LDB(B0, 1, 0); PG8_SCHED; PG8_LDA(At, 1, 0); PG8_STAGE(PG8_SA(0, 1), a2 + hstepA, voffA);
;             PG8_WAIT_L(8); PG8_BAR; PG8_WAIT_L(0); PG8_MMA(0, 0, At, B0); PG8_BAR; PG8_SCHED;
;             PG8_LDB(B1, 1, 1); PG8_STAGE(PG8_SB(1, 0), b3, voffB);
;             PG8_BAR; PG8_WAIT_L(0); PG8_MMA(0, 1, At, B1); PG8_BAR;
	v_mfma_f32_16x16x32_bf16 v[60:63], v[128:131], v[144:147], 0
	s_setprio 1
	v_mfma_f32_16x16x32_bf16 v[56:59], v[136:139], v[144:147], 0
	v_mfma_f32_16x16x32_bf16 v[44:47], v[128:131], v[166:169], 0
	v_mfma_f32_16x16x32_bf16 v[40:43], v[136:139], v[166:169], 0
	v_mfma_f32_16x16x32_bf16 v[28:31], v[128:131], v[178:181], 0
	v_mfma_f32_16x16x32_bf16 v[24:27], v[136:139], v[178:181], 0
	v_mfma_f32_16x16x32_bf16 v[12:15], v[128:131], v[186:189], 0
	v_mfma_f32_16x16x32_bf16 v[8:11], v[136:139], v[186:189], 0
	v_mfma_f32_16x16x32_bf16 v[60:63], v[132:135], v[148:151], v[60:63]
	v_mfma_f32_16x16x32_bf16 v[56:59], v[140:143], v[148:151], v[56:59]
	v_mfma_f32_16x16x32_bf16 v[44:47], v[132:135], v[174:177], v[44:47]
	v_mfma_f32_16x16x32_bf16 v[40:43], v[140:143], v[174:177], v[40:43]
	v_mfma_f32_16x16x32_bf16 v[28:31], v[132:135], v[182:185], v[28:31]
	v_mfma_f32_16x16x32_bf16 v[24:27], v[140:143], v[182:185], v[24:27]
	v_mfma_f32_16x16x32_bf16 v[12:15], v[132:135], v[190:193], v[12:15]
	v_mfma_f32_16x16x32_bf16 v[8:11], v[140:143], v[190:193], v[8:11]
	v_mfma_f32_16x16x32_bf16 v[52:55], v[194:197], v[144:147], 0
	v_mfma_f32_16x16x32_bf16 v[48:51], v[202:205], v[144:147], 0
	s_add_i32 s39, 0, 0x18000
	v_add_u32_e32 v140, s39, v170
	v_mfma_f32_16x16x32_bf16 v[36:39], v[194:197], v[166:169], 0
	v_mfma_f32_16x16x32_bf16 v[32:35], v[202:205], v[166:169], 0
	v_mfma_f32_16x16x32_bf16 v[20:23], v[194:197], v[178:181], 0
	v_mfma_f32_16x16x32_bf16 v[16:19], v[202:205], v[178:181], 0
	v_mfma_f32_16x16x32_bf16 v[4:7], v[194:197], v[186:189], 0
	v_mfma_f32_16x16x32_bf16 v[0:3], v[202:205], v[186:189], 0
	v_mfma_f32_16x16x32_bf16 v[52:55], v[198:201], v[148:151], v[52:55]
	v_mfma_f32_16x16x32_bf16 v[48:51], v[206:209], v[148:151], v[48:51]
	v_mfma_f32_16x16x32_bf16 v[36:39], v[198:201], v[174:177], v[36:39]
	v_mfma_f32_16x16x32_bf16 v[32:35], v[206:209], v[174:177], v[32:35]
	v_mfma_f32_16x16x32_bf16 v[20:23], v[198:201], v[182:185], v[20:23]
	v_mfma_f32_16x16x32_bf16 v[16:19], v[206:209], v[182:185], v[16:19]
	v_mfma_f32_16x16x32_bf16 v[4:7], v[198:201], v[190:193], v[4:7]
	s_setprio 0
	v_mfma_f32_16x16x32_bf16 v[0:3], v[206:209], v[190:193], v[0:3]
	s_barrier
	ds_read_b128 v[128:131], v140
	ds_read_b128 v[136:139], v140 offset:2048
	ds_read_b128 v[132:135], v140 offset:1024
	ds_read_b128 v[140:143], v140 offset:3072
	s_add_u32 s18, s18, 0x80000
	s_addc_u32 s19, s19, 0
	s_mov_b32 m0, s27
	v_lshl_add_u64 v[194:195], s[18:19], 0, v[156:157]
	ds_read_b128 v[144:147], v172 offset:32768
	ds_read_b128 v[166:169], v172 offset:34816
	ds_read_b128 v[178:181], v172 offset:36864
	ds_read_b128 v[186:189], v172 offset:38912
	ds_read_b128 v[148:151], v172 offset:33792
	ds_read_b128 v[174:177], v172 offset:35840
	ds_read_b128 v[182:185], v172 offset:37888
	ds_read_b128 v[190:193], v172 offset:39936
	global_load_lds_dwordx4 v[194:195], off
	s_mov_b32 m0, s28
	v_lshl_add_u64 v[194:195], s[18:19], 0, v[158:159]
	global_load_lds_dwordx4 v[194:195], off
	s_waitcnt lgkmcnt(8)
	s_barrier
	s_waitcnt lgkmcnt(7)
	v_mfma_f32_16x16x32_bf16 v[124:127], v[128:131], v[144:147], v[124:127]
	s_setprio 1
	v_mfma_f32_16x16x32_bf16 v[120:123], v[136:139], v[144:147], v[120:123]
	s_waitcnt lgkmcnt(6)
	v_mfma_f32_16x16x32_bf16 v[108:111], v[128:131], v[166:169], v[108:111]
	v_mfma_f32_16x16x32_bf16 v[104:107], v[136:139], v[166:169], v[104:107]
	s_waitcnt lgkmcnt(5)
	v_mfma_f32_16x16x32_bf16 v[92:95], v[128:131], v[178:181], v[92:95]
	v_mfma_f32_16x16x32_bf16 v[88:91], v[136:139], v[178:181], v[88:91]
	s_waitcnt lgkmcnt(4)
	v_mfma_f32_16x16x32_bf16 v[76:79], v[128:131], v[186:189], v[76:79]
	v_mfma_f32_16x16x32_bf16 v[72:75], v[136:139], v[186:189], v[72:75]
	s_waitcnt lgkmcnt(3)
	v_mfma_f32_16x16x32_bf16 v[124:127], v[132:135], v[148:151], v[124:127]
	v_mfma_f32_16x16x32_bf16 v[120:123], v[140:143], v[148:151], v[120:123]
	s_waitcnt lgkmcnt(2)
	v_mfma_f32_16x16x32_bf16 v[108:111], v[132:135], v[174:177], v[108:111]
	v_mfma_f32_16x16x32_bf16 v[104:107], v[140:143], v[174:177], v[104:107]
	s_waitcnt lgkmcnt(1)
	v_mfma_f32_16x16x32_bf16 v[92:95], v[132:135], v[182:185], v[92:95]
	v_mfma_f32_16x16x32_bf16 v[88:91], v[140:143], v[182:185], v[88:91]
	s_waitcnt lgkmcnt(0)
	v_mfma_f32_16x16x32_bf16 v[76:79], v[132:135], v[190:193], v[76:79]
	s_setprio 0
	v_mfma_f32_16x16x32_bf16 v[72:75], v[140:143], v[190:193], v[72:75]
	s_barrier
	s_add_i32 s40, 0, 0x1c000
	s_add_u32 s18, s14, 0x4000
	s_addc_u32 s19, s15, 0
	s_add_i32 s39, s39, s23
	v_add_u32_e32 v152, s40, v170
	v_lshl_add_u64 v[210:211], s[18:19], 0, v[156:157]
	s_mov_b32 m0, s39
	ds_read_b128 v[194:197], v152
	ds_read_b128 v[202:205], v152 offset:2048
	ds_read_b128 v[198:201], v152 offset:1024
	ds_read_b128 v[206:209], v152 offset:3072
	global_load_lds_dwordx4 v[210:211], off
	s_add_i32 m0, s39, 0x2000
	v_lshl_add_u64 v[210:211], s[18:19], 0, v[158:159]
	global_load_lds_dwordx4 v[210:211], off
	s_waitcnt lgkmcnt(0)
	s_barrier
	v_mfma_f32_16x16x32_bf16 v[116:119], v[194:197], v[144:147], v[116:119]
	s_setprio 1
	v_mfma_f32_16x16x32_bf16 v[112:115], v[202:205], v[144:147], v[112:115]
	s_mov_b32 m0, s29
	v_lshl_add_u64 v[210:211], s[16:17], 0, v[156:157]
	v_mfma_f32_16x16x32_bf16 v[100:103], v[194:197], v[166:169], v[100:103]
	v_mfma_f32_16x16x32_bf16 v[96:99], v[202:205], v[166:169], v[96:99]
	v_mfma_f32_16x16x32_bf16 v[84:87], v[194:197], v[178:181], v[84:87]
	v_mfma_f32_16x16x32_bf16 v[80:83], v[202:205], v[178:181], v[80:83]
	v_mfma_f32_16x16x32_bf16 v[68:71], v[194:197], v[186:189], v[68:71]
	v_mfma_f32_16x16x32_bf16 v[64:67], v[202:205], v[186:189], v[64:67]
	v_mfma_f32_16x16x32_bf16 v[116:119], v[198:201], v[148:151], v[116:119]
	v_mfma_f32_16x16x32_bf16 v[112:115], v[206:209], v[148:151], v[112:115]
	v_mfma_f32_16x16x32_bf16 v[100:103], v[198:201], v[174:177], v[100:103]
	v_mfma_f32_16x16x32_bf16 v[96:99], v[206:209], v[174:177], v[96:99]
	v_mfma_f32_16x16x32_bf16 v[84:87], v[198:201], v[182:185], v[84:87]
	v_mfma_f32_16x16x32_bf16 v[80:83], v[206:209], v[182:185], v[80:83]
	v_mfma_f32_16x16x32_bf16 v[68:71], v[198:201], v[190:193], v[68:71]
	s_setprio 0
	v_mfma_f32_16x16x32_bf16 v[64:67], v[206:209], v[190:193], v[64:67]
	s_barrier
; #define PG8_STAGE(bufoff, gbase, voff) do { _Pragma("unroll") for (int _i = 0; _i < 2; ++_i) \
;         __builtin_amdgcn_global_load_lds((const unsigned*)((const char*)(gbase) + (voff)[_i]), (LAS unsigned*)(lds + (bufoff) + ldsw + _i * 8192), 16, 0, 0); } while (0)
; #define PG8_LDA(dst, b, h) do { _Pragma("unroll") for (int m = 0; m < 4; ++m) _Pragma("unroll") for (int k = 0; k < 2; ++k) dst[m][k] = *(const LAS bf16x8*)(lds + PG8_SA(b, h) + aoff + m * 2048 + k * 1024); } while (0)
; #define PG8_WAIT_V(n) asm volatile("s_waitcnt vmcnt(" #n ")" ::: "memory")
; #define PG8_WAIT_L(n) asm volatile("s_waitcnt lgkmcnt(" #n ")" ::: "memory")
; #define PG8_BAR __builtin_amdgcn_s_barrier()
; template <class Epi>
; __device__ __forceinline__ void gemm_phase(LAS unsigned char* lds, const Gemm g, const StaticOrder& S, const Epi& E) {
;     ...
;             const bool last = (t == nt - 2);
;             const char* a1 = cA + (size_t)(t + 1) * kstep;
;             const char* a2 = last ? nA : cA + (size_t)(t + 2) * kstep; const char* b2 = last ? nB : cB + (size_t)(t + 2) * kstep;
;             const char* a3 = a2 + kstep; const char* b3 = b2 + kstep;
;             PG8_LDB(B0, 0, 0); PG8_SCHED; PG8_LDA(At, 0, 0); PG8_STAGE(PG8_SA(1, 1), a1 + hstepA, voffA);
;             PG8_WAIT_L(8); PG8_BAR; PG8_WAIT_L(0); PG8_MMA(0, 0, At, B0); PG8_BAR; PG8_SCHED;
;             PG8_LDB(B1, 0, 1); PG8_STAGE(PG8_SB(0, 0), b2, voffB);
;             PG8_BAR; PG8_WAIT_L(0); PG8_MMA(0, 1, At, B1); PG8_BAR;
;             PG8_LDA(At, 0, 1); PG8_STAGE(PG8_SA(0, 0), a2, voffA);
;             PG8_BAR; PG8_WAIT_L(0); PG8_MMA(1, 0, At, B0); PG8_BAR; PG8_SCHED;
;             PG8_STAGE(PG8_SB(0, 1), b2 + hstepB, voffB);
;             PG8_WAIT_V(6); PG8_BAR; PG8_MMA(1, 1, At, B1); PG8_BAR;
;             PG8_LDB(B0, 1, 0); PG8_SCHED; PG8_LDA(At, 1, 0); PG8_STAGE(PG8_SA(0, 1), a2 + hstepA, voffA);
;             PG8_WAIT_L(8); PG8_BAR; PG8_WAIT_L(0); PG8_MMA(0, 0, At, B0); PG8_BAR; PG8_SCHED;
;             PG8_LDB(B1, 1, 1); PG8_STAGE(PG8_SB(1, 0), b3, voffB);
;             PG8_BAR; PG8_WAIT_L(0); PG8_MMA(0, 1, At, B1); PG8_BAR;
;             PG8_LDA(At, 1, 1); PG8_STAGE(PG8_SA(1, 0), a3, voffA);
;             PG8_BAR; PG8_WAIT_L(0); PG8_MMA(1, 0, At, B0); PG8_BAR; PG8_SCHED;
;             PG8_STAGE(PG8_SB(1, 1), b3 + hstepB, voffB);
;             PG8_WAIT_V(6); PG8_BAR; PG8_MMA(1, 1, At, B1); PG8_BAR;
	ds_read_b128 v[144:147], v172 offset:49152
	ds_read_b128 v[166:169], v172 offset:51200
	ds_read_b128 v[178:181], v172 offset:53248
	ds_read_b128 v[186:189], v172 offset:55296
	ds_read_b128 v[148:151], v172 offset:50176
	ds_read_b128 v[174:177], v172 offset:52224
	ds_read_b128 v[182:185], v172 offset:54272
	ds_read_b128 v[190:193], v172 offset:56320
	global_load_lds_dwordx4 v[210:211], off
	s_mov_b32 m0, s30
	v_lshl_add_u64 v[210:211], s[16:17], 0, v[158:159]
	global_load_lds_dwordx4 v[210:211], off
	s_add_u32 s14, s14, 0x84000
	s_addc_u32 s15, s15, 0
	s_add_i32 s16, s40, s23
	s_mov_b32 m0, s16
	v_lshl_add_u64 v[210:211], s[14:15], 0, v[156:157]
	global_load_lds_dwordx4 v[210:211], off
	s_add_i32 m0, s16, 0x2000
	v_lshl_add_u64 v[210:211], s[14:15], 0, v[158:159]
	global_load_lds_dwordx4 v[210:211], off
	s_waitcnt vmcnt(6)
	s_waitcnt lgkmcnt(0)
	s_barrier
	v_mfma_f32_16x16x32_bf16 v[60:63], v[128:131], v[144:147], v[60:63]
	s_setprio 1
	v_mfma_f32_16x16x32_bf16 v[56:59], v[136:139], v[144:147], v[56:59]
	v_mfma_f32_16x16x32_bf16 v[44:47], v[128:131], v[166:169], v[44:47]
	v_mfma_f32_16x16x32_bf16 v[40:43], v[136:139], v[166:169], v[40:43]
	v_mfma_f32_16x16x32_bf16 v[28:31], v[128:131], v[178:181], v[28:31]
	v_mfma_f32_16x16x32_bf16 v[24:27], v[136:139], v[178:181], v[24:27]
	v_mfma_f32_16x16x32_bf16 v[12:15], v[128:131], v[186:189], v[12:15]
	v_mfma_f32_16x16x32_bf16 v[8:11], v[136:139], v[186:189], v[8:11]
	v_mfma_f32_16x16x32_bf16 v[60:63], v[132:135], v[148:151], v[60:63]
	v_mfma_f32_16x16x32_bf16 v[56:59], v[140:143], v[148:151], v[56:59]
	v_mfma_f32_16x16x32_bf16 v[44:47], v[132:135], v[174:177], v[44:47]
	v_mfma_f32_16x16x32_bf16 v[40:43], v[140:143], v[174:177], v[40:43]
	v_mfma_f32_16x16x32_bf16 v[28:31], v[132:135], v[182:185], v[28:31]
	v_mfma_f32_16x16x32_bf16 v[24:27], v[140:143], v[182:185], v[24:27]
	v_mfma_f32_16x16x32_bf16 v[12:15], v[132:135], v[190:193], v[12:15]
	v_mfma_f32_16x16x32_bf16 v[8:11], v[140:143], v[190:193], v[8:11]
	v_mfma_f32_16x16x32_bf16 v[52:55], v[194:197], v[144:147], v[52:55]
	v_mfma_f32_16x16x32_bf16 v[48:51], v[202:205], v[144:147], v[48:51]
	s_add_i32 s38, s38, 2
	s_add_u32 s12, s12, 0x8000
	s_addc_u32 s13, s13, 0
	s_add_u32 s36, s36, 0x8000
	s_addc_u32 s37, s37, 0
	v_mfma_f32_16x16x32_bf16 v[36:39], v[194:197], v[166:169], v[36:39]
	v_mfma_f32_16x16x32_bf16 v[32:35], v[202:205], v[166:169], v[32:35]
	v_mfma_f32_16x16x32_bf16 v[20:23], v[194:197], v[178:181], v[20:23]
	v_mfma_f32_16x16x32_bf16 v[16:19], v[202:205], v[178:181], v[16:19]
	v_mfma_f32_16x16x32_bf16 v[4:7], v[194:197], v[186:189], v[4:7]
	v_mfma_f32_16x16x32_bf16 v[0:3], v[202:205], v[186:189], v[0:3]
	v_mfma_f32_16x16x32_bf16 v[52:55], v[198:201], v[148:151], v[52:55]
	v_mfma_f32_16x16x32_bf16 v[48:51], v[206:209], v[148:151], v[48:51]
	v_mfma_f32_16x16x32_bf16 v[36:39], v[198:201], v[174:177], v[36:39]
	v_mfma_f32_16x16x32_bf16 v[32:35], v[206:209], v[174:177], v[32:35]
	v_mfma_f32_16x16x32_bf16 v[20:23], v[198:201], v[182:185], v[20:23]
	v_mfma_f32_16x16x32_bf16 v[16:19], v[206:209], v[182:185], v[16:19]
	v_mfma_f32_16x16x32_bf16 v[4:7], v[198:201], v[190:193], v[4:7]
	s_cmp_gt_u32 s38, 29
	s_setprio 0
	v_mfma_f32_16x16x32_bf16 v[0:3], v[206:209], v[190:193], v[0:3]
	s_barrier
	s_cbranch_scc0 .LBB0_247
	s_branch .Lpeel_done_247
.LBB0_247:
	s_add_u32 s14, s12, 0xfff84000
	s_addc_u32 s15, s13, -1
	s_cmp_eq_u32 s38, 28
	s_cselect_b32 s18, s11, s14
	s_cselect_b32 s19, s5, s15
	s_cselect_b32 s14, s35, s36
	s_cselect_b32 s15, s3, s37
	s_add_u32 s16, s18, 0x4000
	s_addc_u32 s17, s19, 0
	s_add_i32 s39, 0, 0x10000
	v_add_u32_e32 v140, s39, v170
	ds_read_b128 v[128:131], v140
	ds_read_b128 v[136:139], v140 offset:2048
	ds_read_b128 v[132:135], v140 offset:1024
	ds_read_b128 v[140:143], v140 offset:3072
	v_lshl_add_u64 v[194:195], s[12:13], 0, v[156:157]
	s_add_i32 m0, s25, 0xc000
	ds_read_b128 v[144:147], v172
	ds_read_b128 v[166:169], v172 offset:2048
	ds_read_b128 v[178:181], v172 offset:4096
	ds_read_b128 v[186:189], v172 offset:6144
	ds_read_b128 v[148:151], v172 offset:1024
	ds_read_b128 v[174:177], v172 offset:3072
	ds_read_b128 v[182:185], v172 offset:5120
	ds_read_b128 v[190:193], v172 offset:7168
	global_load_lds_dwordx4 v[194:195], off
	s_add_i32 m0, s25, 0xe000
	v_lshl_add_u64 v[194:195], s[12:13], 0, v[158:159]
	global_load_lds_dwordx4 v[194:195], off
	s_waitcnt lgkmcnt(8)
	s_barrier
	s_waitcnt lgkmcnt(7)
	v_mfma_f32_16x16x32_bf16 v[124:127], v[128:131], v[144:147], v[124:127]
	s_setprio 1
	v_mfma_f32_16x16x32_bf16 v[120:123], v[136:139], v[144:147], v[120:123]
	s_waitcnt lgkmcnt(6)
	v_mfma_f32_16x16x32_bf16 v[108:111], v[128:131], v[166:169], v[108:111]
	v_mfma_f32_16x16x32_bf16 v[104:107], v[136:139], v[166:169], v[104:107]
	s_waitcnt lgkmcnt(5)
	v_mfma_f32_16x16x32_bf16 v[92:95], v[128:131], v[178:181], v[92:95]
	v_mfma_f32_16x16x32_bf16 v[88:91], v[136:139], v[178:181], v[88:91]
	s_waitcnt lgkmcnt(4)
	v_mfma_f32_16x16x32_bf16 v[76:79], v[128:131], v[186:189], v[76:79]
	v_mfma_f32_16x16x32_bf16 v[72:75], v[136:139], v[186:189], v[72:75]
	s_waitcnt lgkmcnt(3)
	v_mfma_f32_16x16x32_bf16 v[124:127], v[132:135], v[148:151], v[124:127]
	v_mfma_f32_16x16x32_bf16 v[120:123], v[140:143], v[148:151], v[120:123]
	s_waitcnt lgkmcnt(2)
	v_mfma_f32_16x16x32_bf16 v[108:111], v[132:135], v[174:177], v[108:111]
	v_mfma_f32_16x16x32_bf16 v[104:107], v[140:143], v[174:177], v[104:107]
	s_waitcnt lgkmcnt(1)
	v_mfma_f32_16x16x32_bf16 v[92:95], v[132:135], v[182:185], v[92:95]
	v_mfma_f32_16x16x32_bf16 v[88:91], v[140:143], v[182:185], v[88:91]
	s_waitcnt lgkmcnt(0)
	v_mfma_f32_16x16x32_bf16 v[76:79], v[132:135], v[190:193], v[76:79]
	s_setprio 0
	v_mfma_f32_16x16x32_bf16 v[72:75], v[140:143], v[190:193], v[72:75]
	s_barrier
; #define PG8_STAGE(bufoff, gbase, voff) do { _Pragma("unroll") for (int _i = 0; _i < 2; ++_i) \
;         __builtin_amdgcn_global_load_lds((const unsigned*)((const char*)(gbase) + (voff)[_i]), (LAS unsigned*)(lds + (bufoff) + ldsw + _i * 8192), 16, 0, 0); } while (0)
; #define PG8_LDA(dst, b, h) do { _Pragma("unroll") for (int m = 0; m < 4; ++m) _Pragma("unroll") for (int k = 0; k < 2; ++k) dst[m][k] = *(const LAS bf16x8*)(lds + PG8_SA(b, h) + aoff + m * 2048 + k * 1024); } while (0)
; #define PG8_LDB(dst, b, h) do { _Pragma("unroll") for (int n = 0; n < 2; ++n) _Pragma("unroll") for (int k = 0; k < 2; ++k) dst[n][k] = *(const LAS bf16x8*)(lds + PG8_SB(b, h) + boff + n * 2048 + k * 1024); } while (0)
; #define PG8_MMA(ai, bj, At, Bt) do { __builtin_amdgcn_s_setprio(1); _Pragma("unroll") for (int m = 0; m < 4; ++m) _Pragma("unroll") for (int n = 0; n < 2; ++n) _Pragma("unroll") for (int k = 0; k < 2; ++k) \
;         acc[ai][bj][m][n] = __builtin_amdgcn_mfma_f32_16x16x32_bf16(Bt[n][k], At[m][k], acc[ai][bj][m][n], 0, 0, 0); __builtin_amdgcn_s_setprio(0); } while (0)
; #define PG8_WAIT_V(n) asm volatile("s_waitcnt vmcnt(" #n ")" ::: "memory")
; #define PG8_WAIT_L(n) asm volatile("s_waitcnt lgkmcnt(" #n ")" ::: "memory")
; #define PG8_BAR __builtin_amdgcn_s_barrier()
; #define PG8_SCHED __builtin_amdgcn_sched_barrier(0)
; template <class Epi>
; __device__ __forceinline__ void gemm_phase(LAS unsigned char* lds, const Gemm g, const StaticOrder& S, const Epi& E) {
;     ...
;             PG8_LDB(B1, 0, 1); PG8_STAGE(PG8_SB(0, 0), b2, voffB);
;             PG8_BAR; PG8_WAIT_L(0); PG8_MMA(0, 1, At, B1); PG8_BAR;
;             PG8_LDA(At, 0, 1); PG8_STAGE(PG8_SA(0, 0), a2, voffA);
;             PG8_BAR; PG8_WAIT_L(0); PG8_MMA(1, 0, At, B0); PG8_BAR; PG8_SCHED;
;             PG8_STAGE(PG8_SB(0, 1), b2 + hstepB, voffB);
;             PG8_WAIT_V(6); PG8_BAR; PG8_MMA(1, 1, At, B1); PG8_BAR;
;             PG8_LDB(B0, 1, 0); PG8_SCHED; PG8_LDA(At, 1, 0); PG8_STAGE(PG8_SA(0, 1), a2 + hstepA, voffA);
;             PG8_WAIT_L(8); PG8_BAR; PG8_WAIT_L(0); PG8_MMA(0, 0, At, B0); PG8_BAR; PG8_SCHED;
	s_add_i32 s42, 0, 0x14000
	s_add_i32 s39, s39, s23
	v_add_u32_e32 v152, s42, v170
	v_lshl_add_u64 v[210:211], s[14:15], 0, v[156:157]
	s_mov_b32 m0, s39
	ds_read_b128 v[194:197], v152
	ds_read_b128 v[202:205], v152 offset:2048
	ds_read_b128 v[198:201], v152 offset:1024
	ds_read_b128 v[206:209], v152 offset:3072
	global_load_lds_dwordx4 v[210:211], off
	s_add_i32 m0, s39, 0x2000
	v_lshl_add_u64 v[210:211], s[14:15], 0, v[158:159]
	global_load_lds_dwordx4 v[210:211], off
	s_waitcnt lgkmcnt(0)
	s_barrier
	v_mfma_f32_16x16x32_bf16 v[116:119], v[194:197], v[144:147], v[116:119]
	s_setprio 1
	v_mfma_f32_16x16x32_bf16 v[112:115], v[202:205], v[144:147], v[112:115]
	s_mov_b32 m0, s25
	v_lshl_add_u64 v[210:211], s[18:19], 0, v[156:157]
	v_mfma_f32_16x16x32_bf16 v[100:103], v[194:197], v[166:169], v[100:103]
	v_mfma_f32_16x16x32_bf16 v[96:99], v[202:205], v[166:169], v[96:99]
	v_mfma_f32_16x16x32_bf16 v[84:87], v[194:197], v[178:181], v[84:87]
	v_mfma_f32_16x16x32_bf16 v[80:83], v[202:205], v[178:181], v[80:83]
	v_mfma_f32_16x16x32_bf16 v[68:71], v[194:197], v[186:189], v[68:71]
	v_mfma_f32_16x16x32_bf16 v[64:67], v[202:205], v[186:189], v[64:67]
	v_mfma_f32_16x16x32_bf16 v[116:119], v[198:201], v[148:151], v[116:119]
	v_mfma_f32_16x16x32_bf16 v[112:115], v[206:209], v[148:151], v[112:115]
	v_mfma_f32_16x16x32_bf16 v[100:103], v[198:201], v[174:177], v[100:103]
	v_mfma_f32_16x16x32_bf16 v[96:99], v[206:209], v[174:177], v[96:99]
	v_mfma_f32_16x16x32_bf16 v[84:87], v[198:201], v[182:185], v[84:87]
	v_mfma_f32_16x16x32_bf16 v[80:83], v[206:209], v[182:185], v[80:83]
	v_mfma_f32_16x16x32_bf16 v[68:71], v[198:201], v[190:193], v[68:71]
	s_setprio 0
	v_mfma_f32_16x16x32_bf16 v[64:67], v[206:209], v[190:193], v[64:67]
	s_barrier
	ds_read_b128 v[144:147], v172 offset:16384
	ds_read_b128 v[166:169], v172 offset:18432
	ds_read_b128 v[178:181], v172 offset:20480
	ds_read_b128 v[186:189], v172 offset:22528
	ds_read_b128 v[148:151], v172 offset:17408
	ds_read_b128 v[174:177], v172 offset:19456
	ds_read_b128 v[182:185], v172 offset:21504
	ds_read_b128 v[190:193], v172 offset:23552
	global_load_lds_dwordx4 v[210:211], off
	s_mov_b32 m0, s26
	v_lshl_add_u64 v[210:211], s[18:19], 0, v[158:159]
	global_load_lds_dwordx4 v[210:211], off
	s_add_u32 s40, s14, 0x80000
	s_addc_u32 s41, s15, 0
	s_add_i32 s39, s42, s23
	s_mov_b32 m0, s39
	v_lshl_add_u64 v[210:211], s[40:41], 0, v[156:157]
	global_load_lds_dwordx4 v[210:211], off
	s_add_i32 m0, s39, 0x2000
	v_lshl_add_u64 v[210:211], s[40:41], 0, v[158:159]
	global_load_lds_dwordx4 v[210:211], off
	s_waitcnt vmcnt(6)
	s_waitcnt lgkmcnt(0)
	s_barrier
	v_mfma_f32_16x16x32_bf16 v[60:63], v[128:131], v[144:147], v[60:63]
	s_setprio 1
	v_mfma_f32_16x16x32_bf16 v[56:59], v[136:139], v[144:147], v[56:59]
	v_mfma_f32_16x16x32_bf16 v[44:47], v[128:131], v[166:169], v[44:47]
	v_mfma_f32_16x16x32_bf16 v[40:43], v[136:139], v[166:169], v[40:43]
	v_mfma_f32_16x16x32_bf16 v[28:31], v[128:131], v[178:181], v[28:31]
	v_mfma_f32_16x16x32_bf16 v[24:27], v[136:139], v[178:181], v[24:27]
	v_mfma_f32_16x16x32_bf16 v[12:15], v[128:131], v[186:189], v[12:15]
	v_mfma_f32_16x16x32_bf16 v[8:11], v[136:139], v[186:189], v[8:11]
	v_mfma_f32_16x16x32_bf16 v[60:63], v[132:135], v[148:151], v[60:63]
	v_mfma_f32_16x16x32_bf16 v[56:59], v[140:143], v[148:151], v[56:59]
	v_mfma_f32_16x16x32_bf16 v[44:47], v[132:135], v[174:177], v[44:47]
	v_mfma_f32_16x16x32_bf16 v[40:43], v[140:143], v[174:177], v[40:43]
	v_mfma_f32_16x16x32_bf16 v[28:31], v[132:135], v[182:185], v[28:31]
	v_mfma_f32_16x16x32_bf16 v[24:27], v[140:143], v[182:185], v[24:27]
	v_mfma_f32_16x16x32_bf16 v[12:15], v[132:135], v[190:193], v[12:15]
	v_mfma_f32_16x16x32_bf16 v[8:11], v[140:143], v[190:193], v[8:11]
	v_mfma_f32_16x16x32_bf16 v[52:55], v[194:197], v[144:147], v[52:55]
	v_mfma_f32_16x16x32_bf16 v[48:51], v[202:205], v[144:147], v[48:51]
	s_add_i32 s39, 0, 0x18000
	v_add_u32_e32 v140, s39, v170
	v_mfma_f32_16x16x32_bf16 v[36:39], v[194:197], v[166:169], v[36:39]
	v_mfma_f32_16x16x32_bf16 v[32:35], v[202:205], v[166:169], v[32:35]
	v_mfma_f32_16x16x32_bf16 v[20:23], v[194:197], v[178:181], v[20:23]
	v_mfma_f32_16x16x32_bf16 v[16:19], v[202:205], v[178:181], v[16:19]
	v_mfma_f32_16x16x32_bf16 v[4:7], v[194:197], v[186:189], v[4:7]
	v_mfma_f32_16x16x32_bf16 v[0:3], v[202:205], v[186:189], v[0:3]
	v_mfma_f32_16x16x32_bf16 v[52:55], v[198:201], v[148:151], v[52:55]
	v_mfma_f32_16x16x32_bf16 v[48:51], v[206:209], v[148:151], v[48:51]
	v_mfma_f32_16x16x32_bf16 v[36:39], v[198:201], v[174:177], v[36:39]
	v_mfma_f32_16x16x32_bf16 v[32:35], v[206:209], v[174:177], v[32:35]
	v_mfma_f32_16x16x32_bf16 v[20:23], v[198:201], v[182:185], v[20:23]
	v_mfma_f32_16x16x32_bf16 v[16:19], v[206:209], v[182:185], v[16:19]
	v_mfma_f32_16x16x32_bf16 v[4:7], v[198:201], v[190:193], v[4:7]
	s_setprio 0
	v_mfma_f32_16x16x32_bf16 v[0:3], v[206:209], v[190:193], v[0:3]
	s_barrier
	ds_read_b128 v[128:131], v140
	ds_read_b128 v[136:139], v140 offset:2048
	ds_read_b128 v[132:135], v140 offset:1024
	ds_read_b128 v[140:143], v140 offset:3072
	s_add_u32 s18, s18, 0x80000
	s_addc_u32 s19, s19, 0
	s_mov_b32 m0, s27
	v_lshl_add_u64 v[194:195], s[18:19], 0, v[156:157]
	ds_read_b128 v[144:147], v172 offset:32768
	ds_read_b128 v[166:169], v172 offset:34816
	ds_read_b128 v[178:181], v172 offset:36864
	ds_read_b128 v[186:189], v172 offset:38912
	ds_read_b128 v[148:151], v172 offset:33792
	ds_read_b128 v[174:177], v172 offset:35840
	ds_read_b128 v[182:185], v172 offset:37888
	ds_read_b128 v[190:193], v172 offset:39936
	global_load_lds_dwordx4 v[194:195], off
	s_mov_b32 m0, s28
	v_lshl_add_u64 v[194:195], s[18:19], 0, v[158:159]
	global_load_lds_dwordx4 v[194:195], off
	s_waitcnt lgkmcnt(8)
	s_barrier
; #define PG8_STAGE(bufoff, gbase, voff) do { _Pragma("unroll") for (int _i = 0; _i < 2; ++_i) \
;         __builtin_amdgcn_global_load_lds((const unsigned*)((const char*)(gbase) + (voff)[_i]), (LAS unsigned*)(lds + (bufoff) + ldsw + _i * 8192), 16, 0, 0); } while (0)
; #define PG8_LDA(dst, b, h) do { _Pragma("unroll") for (int m = 0; m < 4; ++m) _Pragma("unroll") for (int k = 0; k < 2; ++k) dst[m][k] = *(const LAS bf16x8*)(lds + PG8_SA(b, h) + aoff + m * 2048 + k * 1024); } while (0)
; #define PG8_LDB(dst, b, h) do { _Pragma("unroll") for (int n = 0; n < 2; ++n) _Pragma("unroll") for (int k = 0; k < 2; ++k) dst[n][k] = *(const LAS bf16x8*)(lds + PG8_SB(b, h) + boff + n * 2048 + k * 1024); } while (0)
; #define PG8_MMA(ai, bj, At, Bt) do { __builtin_amdgcn_s_setprio(1); _Pragma("unroll") for (int m = 0; m < 4; ++m) _Pragma("unroll") for (int n = 0; n < 2; ++n) _Pragma("unroll") for (int k = 0; k < 2; ++k) \
;         acc[ai][bj][m][n] = __builtin_amdgcn_mfma_f32_16x16x32_bf16(Bt[n][k], At[m][k], acc[ai][bj][m][n], 0, 0, 0); __builtin_amdgcn_s_setprio(0); } while (0)
; #define PG8_WAIT_V(n) asm volatile("s_waitcnt vmcnt(" #n ")" ::: "memory")
; #define PG8_WAIT_L(n) asm volatile("s_waitcnt lgkmcnt(" #n ")" ::: "memory")
; #define PG8_BAR __builtin_amdgcn_s_barrier()
; #define PG8_SCHED __builtin_amdgcn_sched_barrier(0)
; template <class Epi>
; __device__ __forceinline__ void gemm_phase(LAS unsigned char* lds, const Gemm g, const StaticOrder& S, const Epi& E) {
;     ...
;             PG8_WAIT_L(8); PG8_BAR; PG8_WAIT_L(0); PG8_MMA(0, 0, At, B0); PG8_BAR; PG8_SCHED;
;             PG8_LDB(B1, 1, 1); PG8_STAGE(PG8_SB(1, 0), b3, voffB);
;             PG8_BAR; PG8_WAIT_L(0); PG8_MMA(0, 1, At, B1); PG8_BAR;
;             PG8_LDA(At, 1, 1); PG8_STAGE(PG8_SA(1, 0), a3, voffA);
;             PG8_BAR; PG8_WAIT_L(0); PG8_MMA(1, 0, At, B0); PG8_BAR; PG8_SCHED;
;             PG8_STAGE(PG8_SB(1, 1), b3 + hstepB, voffB);
;             PG8_WAIT_V(6); PG8_BAR; PG8_MMA(1, 1, At, B1); PG8_BAR;
	s_waitcnt lgkmcnt(7)
	v_mfma_f32_16x16x32_bf16 v[124:127], v[128:131], v[144:147], v[124:127]
	s_setprio 1
	v_mfma_f32_16x16x32_bf16 v[120:123], v[136:139], v[144:147], v[120:123]
	s_waitcnt lgkmcnt(6)
	v_mfma_f32_16x16x32_bf16 v[108:111], v[128:131], v[166:169], v[108:111]
	v_mfma_f32_16x16x32_bf16 v[104:107], v[136:139], v[166:169], v[104:107]
	s_waitcnt lgkmcnt(5)
	v_mfma_f32_16x16x32_bf16 v[92:95], v[128:131], v[178:181], v[92:95]
	v_mfma_f32_16x16x32_bf16 v[88:91], v[136:139], v[178:181], v[88:91]
	s_waitcnt lgkmcnt(4)
	v_mfma_f32_16x16x32_bf16 v[76:79], v[128:131], v[186:189], v[76:79]
	v_mfma_f32_16x16x32_bf16 v[72:75], v[136:139], v[186:189], v[72:75]
	s_waitcnt lgkmcnt(3)
	v_mfma_f32_16x16x32_bf16 v[124:127], v[132:135], v[148:151], v[124:127]
	v_mfma_f32_16x16x32_bf16 v[120:123], v[140:143], v[148:151], v[120:123]
	s_waitcnt lgkmcnt(2)
	v_mfma_f32_16x16x32_bf16 v[108:111], v[132:135], v[174:177], v[108:111]
	v_mfma_f32_16x16x32_bf16 v[104:107], v[140:143], v[174:177], v[104:107]
	s_waitcnt lgkmcnt(1)
	v_mfma_f32_16x16x32_bf16 v[92:95], v[132:135], v[182:185], v[92:95]
	v_mfma_f32_16x16x32_bf16 v[88:91], v[140:143], v[182:185], v[88:91]
	s_waitcnt lgkmcnt(0)
	v_mfma_f32_16x16x32_bf16 v[76:79], v[132:135], v[190:193], v[76:79]
	s_setprio 0
	v_mfma_f32_16x16x32_bf16 v[72:75], v[140:143], v[190:193], v[72:75]
	s_barrier
	s_add_i32 s40, 0, 0x1c000
	s_add_u32 s18, s14, 0x4000
	s_addc_u32 s19, s15, 0
	s_add_i32 s39, s39, s23
	v_add_u32_e32 v152, s40, v170
	v_lshl_add_u64 v[210:211], s[18:19], 0, v[156:157]
	s_mov_b32 m0, s39
	ds_read_b128 v[194:197], v152
	ds_read_b128 v[202:205], v152 offset:2048
	ds_read_b128 v[198:201], v152 offset:1024
	ds_read_b128 v[206:209], v152 offset:3072
	global_load_lds_dwordx4 v[210:211], off
	s_add_i32 m0, s39, 0x2000
	v_lshl_add_u64 v[210:211], s[18:19], 0, v[158:159]
	global_load_lds_dwordx4 v[210:211], off
	s_waitcnt lgkmcnt(0)
	s_barrier
	v_mfma_f32_16x16x32_bf16 v[116:119], v[194:197], v[144:147], v[116:119]
	s_setprio 1
	v_mfma_f32_16x16x32_bf16 v[112:115], v[202:205], v[144:147], v[112:115]
	s_mov_b32 m0, s29
	v_lshl_add_u64 v[210:211], s[16:17], 0, v[156:157]
	v_mfma_f32_16x16x32_bf16 v[100:103], v[194:197], v[166:169], v[100:103]
	v_mfma_f32_16x16x32_bf16 v[96:99], v[202:205], v[166:169], v[96:99]
	v_mfma_f32_16x16x32_bf16 v[84:87], v[194:197], v[178:181], v[84:87]
	v_mfma_f32_16x16x32_bf16 v[80:83], v[202:205], v[178:181], v[80:83]
	v_mfma_f32_16x16x32_bf16 v[68:71], v[194:197], v[186:189], v[68:71]
	v_mfma_f32_16x16x32_bf16 v[64:67], v[202:205], v[186:189], v[64:67]
	v_mfma_f32_16x16x32_bf16 v[116:119], v[198:201], v[148:151], v[116:119]
	v_mfma_f32_16x16x32_bf16 v[112:115], v[206:209], v[148:151], v[112:115]
	v_mfma_f32_16x16x32_bf16 v[100:103], v[198:201], v[174:177], v[100:103]
	v_mfma_f32_16x16x32_bf16 v[96:99], v[206:209], v[174:177], v[96:99]
	v_mfma_f32_16x16x32_bf16 v[84:87], v[198:201], v[182:185], v[84:87]
	v_mfma_f32_16x16x32_bf16 v[80:83], v[206:209], v[182:185], v[80:83]
	v_mfma_f32_16x16x32_bf16 v[68:71], v[198:201], v[190:193], v[68:71]
	s_setprio 0
	v_mfma_f32_16x16x32_bf16 v[64:67], v[206:209], v[190:193], v[64:67]
	s_barrier
	ds_read_b128 v[144:147], v172 offset:49152
	ds_read_b128 v[166:169], v172 offset:51200
	ds_read_b128 v[178:181], v172 offset:53248
	ds_read_b128 v[186:189], v172 offset:55296
	ds_read_b128 v[148:151], v172 offset:50176
	ds_read_b128 v[174:177], v172 offset:52224
	ds_read_b128 v[182:185], v172 offset:54272
	ds_read_b128 v[190:193], v172 offset:56320
	global_load_lds_dwordx4 v[210:211], off
	s_mov_b32 m0, s30
	v_lshl_add_u64 v[210:211], s[16:17], 0, v[158:159]
	global_load_lds_dwordx4 v[210:211], off
	s_add_u32 s14, s14, 0x84000
	s_addc_u32 s15, s15, 0
	s_add_i32 s16, s40, s23
	s_mov_b32 m0, s16
	v_lshl_add_u64 v[210:211], s[14:15], 0, v[156:157]
	global_load_lds_dwordx4 v[210:211], off
	s_add_i32 m0, s16, 0x2000
	v_lshl_add_u64 v[210:211], s[14:15], 0, v[158:159]
	global_load_lds_dwordx4 v[210:211], off
	s_waitcnt vmcnt(6)
	s_waitcnt lgkmcnt(0)
	s_barrier
	v_mfma_f32_16x16x32_bf16 v[60:63], v[128:131], v[144:147], v[60:63]
	s_setprio 1
	v_mfma_f32_16x16x32_bf16 v[56:59], v[136:139], v[144:147], v[56:59]
	v_mfma_f32_16x16x32_bf16 v[44:47], v[128:131], v[166:169], v[44:47]
	v_mfma_f32_16x16x32_bf16 v[40:43], v[136:139], v[166:169], v[40:43]
	v_mfma_f32_16x16x32_bf16 v[28:31], v[128:131], v[178:181], v[28:31]
	v_mfma_f32_16x16x32_bf16 v[24:27], v[136:139], v[178:181], v[24:27]
	v_mfma_f32_16x16x32_bf16 v[12:15], v[128:131], v[186:189], v[12:15]
	v_mfma_f32_16x16x32_bf16 v[8:11], v[136:139], v[186:189], v[8:11]
	v_mfma_f32_16x16x32_bf16 v[60:63], v[132:135], v[148:151], v[60:63]
	v_mfma_f32_16x16x32_bf16 v[56:59], v[140:143], v[148:151], v[56:59]
	v_mfma_f32_16x16x32_bf16 v[44:47], v[132:135], v[174:177], v[44:47]
	v_mfma_f32_16x16x32_bf16 v[40:43], v[140:143], v[174:177], v[40:43]
	v_mfma_f32_16x16x32_bf16 v[28:31], v[132:135], v[182:185], v[28:31]
	v_mfma_f32_16x16x32_bf16 v[24:27], v[140:143], v[182:185], v[24:27]
	v_mfma_f32_16x16x32_bf16 v[12:15], v[132:135], v[190:193], v[12:15]
	v_mfma_f32_16x16x32_bf16 v[8:11], v[140:143], v[190:193], v[8:11]
	v_mfma_f32_16x16x32_bf16 v[52:55], v[194:197], v[144:147], v[52:55]
	v_mfma_f32_16x16x32_bf16 v[48:51], v[202:205], v[144:147], v[48:51]
	s_add_i32 s38, s38, 2
	s_add_u32 s12, s12, 0x8000
	s_addc_u32 s13, s13, 0
	s_add_u32 s36, s36, 0x8000
	s_addc_u32 s37, s37, 0
	v_mfma_f32_16x16x32_bf16 v[36:39], v[194:197], v[166:169], v[36:39]
	v_mfma_f32_16x16x32_bf16 v[32:35], v[202:205], v[166:169], v[32:35]
	v_mfma_f32_16x16x32_bf16 v[20:23], v[194:197], v[178:181], v[20:23]
	v_mfma_f32_16x16x32_bf16 v[16:19], v[202:205], v[178:181], v[16:19]
	v_mfma_f32_16x16x32_bf16 v[4:7], v[194:197], v[186:189], v[4:7]
	v_mfma_f32_16x16x32_bf16 v[0:3], v[202:205], v[186:189], v[0:3]
	v_mfma_f32_16x16x32_bf16 v[52:55], v[198:201], v[148:151], v[52:55]
	v_mfma_f32_16x16x32_bf16 v[48:51], v[206:209], v[148:151], v[48:51]
	v_mfma_f32_16x16x32_bf16 v[36:39], v[198:201], v[174:177], v[36:39]
	v_mfma_f32_16x16x32_bf16 v[32:35], v[206:209], v[174:177], v[32:35]
	v_mfma_f32_16x16x32_bf16 v[20:23], v[198:201], v[182:185], v[20:23]
	v_mfma_f32_16x16x32_bf16 v[16:19], v[206:209], v[182:185], v[16:19]
	v_mfma_f32_16x16x32_bf16 v[4:7], v[198:201], v[190:193], v[4:7]
	s_cmp_gt_u32 s38, 29
	s_setprio 0
	v_mfma_f32_16x16x32_bf16 v[0:3], v[206:209], v[190:193], v[0:3]
	s_barrier
	s_cbranch_scc0 .LBB0_247
